# MLA rescale test shortened: v_cmp_nge + s_cbranch_vccnz instead of v_cmp_ge / s_cmp_eq_u64 vcc,exec / s_cbranch_scc0 (one SALU op fewer on the serial chain per tile)
# baseline (speedup 1.0000x reference)
; __device__ __forceinline__ void finishSM9(f32x16& p0, f32x16& p1, float alpha, float& l_reg, v8i32& p8) {
; #pragma unroll
;   for (int r = 0; r < 16; ++r) { p0[r] = __builtin_amdgcn_exp2f(p0[r]); p1[r] = __builtin_amdgcn_exp2f(p1[r]); }
;   float ps = 0;
; #pragma unroll
;   for (int r = 0; r < 16; ++r) ps += p0[r];
; #pragma unroll
;   for (int r = 0; r < 16; ++r) ps += p1[r];
;   { auto rr = __builtin_amdgcn_permlane32_swap(__float_as_uint(ps), __float_as_uint(ps), false, false);
;     ps = __uint_as_float(rr[0]) + __uint_as_float(rr[1]); }
;   l_reg = l_reg * alpha + ps;
; #pragma unroll
;   for (int g = 0; g < 4; ++g) {
;     int w = __builtin_amdgcn_cvt_pk_fp8_f32(p0[4 * g], p0[4 * g + 1], 0, false); p8[g] = __builtin_amdgcn_cvt_pk_fp8_f32(p0[4 * g + 2], p0[4 * g + 3], w, true);
;     int u = __builtin_amdgcn_cvt_pk_fp8_f32(p1[4 * g], p1[4 * g + 1], 0, false); p8[4 + g] = __builtin_amdgcn_cvt_pk_fp8_f32(p1[4 * g + 2], p1[4 * g + 3], u, true); }
; }
; __device__ __forceinline__ void pv8(f32x16* o, const char* Vt, const v8i32 p8, int r32, int hi) {
;   const int sw = (r32 >> 2) & 3, a0 = r32 * 64 + (((hi * 2) ^ sw) << 4), a1 = r32 * 64 + (((hi * 2 + 1) ^ sw) << 4);
; #pragma unroll
;   for (int d0 = 0; d0 < 4; ++d0) {
;     const v8i32 vf = cat8(*reinterpret_cast<const v4i32*>(Vt + d0 * 2048 + a0), *reinterpret_cast<const v4i32*>(Vt + d0 * 2048 + a1));
;     o[d0] = __builtin_amdgcn_mfma_scale_f32_32x32x64_f8f6f4(p8, vf, o[d0], 0, 0, 0, 127, 0, 127); }
; }
; __device__ __forceinline__ void qkt9(f32x16& p0, f32x16& p1, const char* Kn, const char* Kr, const v8i32* qf, const float init, int r32, int hi) {
; #pragma unroll
;   for (int r = 0; r < 16; ++r) { p0[r] = init; p1[r] = init; }
; #pragma unroll
;   for (int s = 0; s < 2; ++s) { const int c0 = s * 4 + hi * 2;
;     const v8i32 a0 = cat8(*reinterpret_cast<const v4i32*>(Kn + KN8SW(r32, c0)), *reinterpret_cast<const v4i32*>(Kn + KN8SW(r32, c0 + 1)));
;     const v8i32 a1 = cat8(*reinterpret_cast<const v4i32*>(Kn + 4096 + KN8SW(r32, c0)), *reinterpret_cast<const v4i32*>(Kn + 4096 + KN8SW(r32, c0 + 1)));
;     p0 = __builtin_amdgcn_mfma_scale_f32_32x32x64_f8f6f4(a0, qf[s], p0, 0, 0, 0, 127, 0, 124);
;     p1 = __builtin_amdgcn_mfma_scale_f32_32x32x64_f8f6f4(a1, qf[s], p1, 0, 0, 0, 127, 0, 124); }
;   { const int c0 = hi * 2;
.LBB0_1321:
	ds_read_b128 v[114:117], v215 offset:24576
	ds_read_b128 v[118:121], v216 offset:24576
	ds_read_b128 v[222:225], v215 offset:28672
	ds_read_b128 v[226:229], v216 offset:28672
	s_add_i32 m0, s98, 0xa800
	s_nop 0
	global_load_lds_dwordx4 v176, s[18:19]
	s_add_i32 m0, s98, 0xc800
	s_nop 0
	global_load_lds_dwordx4 v178, s[16:17]
	s_add_i32 m0, s98, 0xe800
	s_nop 0
	global_load_lds_dwordx4 v[180:181], off
	v_exp_f32_e32 v0, v82
	v_exp_f32_e32 v177, v83
	v_exp_f32_e32 v179, v84
	v_exp_f32_e32 v254, v85
	v_add_f32_e32 v219, v0, v177
	v_cvt_pk_fp8_f32 v246, v0, v177
	v_add_f32_e32 v219, v179, v219
	v_add_f32_e32 v219, v254, v219
	v_cvt_pk_fp8_f32 v246, v179, v254 op_sel:[0,0,1]
	s_waitcnt lgkmcnt(2)
	v_mfma_scale_f32_32x32x64_f8f6f4 v[114:129], v[114:121], v[146:153], v[230:245], v194, v193 op_sel_hi:[0,0,0]
	v_exp_f32_e32 v0, v86
	v_exp_f32_e32 v177, v87
	v_exp_f32_e32 v179, v88
	v_exp_f32_e32 v254, v89
	v_add_f32_e32 v219, v0, v219
	v_add_f32_e32 v219, v177, v219
	v_cvt_pk_fp8_f32 v247, v0, v177
	v_add_f32_e32 v219, v179, v219
	v_add_f32_e32 v219, v254, v219
	v_cvt_pk_fp8_f32 v247, v179, v254 op_sel:[0,0,1]
	ds_read_b128 v[82:85], v213 offset:24576
	ds_read_b128 v[86:89], v214 offset:24576
	s_waitcnt lgkmcnt(2)
	v_mfma_scale_f32_32x32x64_f8f6f4 v[98:113], v[222:229], v[146:153], v[230:245], v194, v193 op_sel_hi:[0,0,0]
	ds_read_b128 v[222:225], v213 offset:28672
	ds_read_b128 v[226:229], v214 offset:28672
	v_exp_f32_e32 v0, v90
	v_exp_f32_e32 v177, v91
	v_exp_f32_e32 v179, v92
	v_exp_f32_e32 v254, v93
	v_add_f32_e32 v219, v0, v219
	v_add_f32_e32 v219, v177, v219
	v_cvt_pk_fp8_f32 v248, v0, v177
	v_add_f32_e32 v219, v179, v219
	v_add_f32_e32 v219, v254, v219
	v_cvt_pk_fp8_f32 v248, v179, v254 op_sel:[0,0,1]
	v_exp_f32_e32 v0, v94
	v_exp_f32_e32 v177, v95
	v_exp_f32_e32 v179, v96
	v_exp_f32_e32 v254, v97
	v_add_f32_e32 v219, v0, v219
	v_add_f32_e32 v219, v177, v219
	v_cvt_pk_fp8_f32 v249, v0, v177
	v_add_f32_e32 v219, v179, v219
	v_add_f32_e32 v219, v254, v219
	v_cvt_pk_fp8_f32 v249, v179, v254 op_sel:[0,0,1]
	ds_read_b128 v[90:93], v185 offset:36864
	ds_read_b128 v[94:97], v186 offset:36864
	s_waitcnt lgkmcnt(4)
	v_mfma_scale_f32_32x32x64_f8f6f4 v[114:129], v[82:89], v[138:145], v[114:129], v194, v193 op_sel_hi:[0,0,0]
	v_exp_f32_e32 v0, v66
	v_exp_f32_e32 v177, v67
	v_exp_f32_e32 v179, v68
	v_exp_f32_e32 v254, v69
	v_add_f32_e32 v219, v0, v219
	v_add_f32_e32 v219, v177, v219
	v_cvt_pk_fp8_f32 v250, v0, v177
	v_add_f32_e32 v219, v179, v219
	v_add_f32_e32 v219, v254, v219
	v_cvt_pk_fp8_f32 v250, v179, v254 op_sel:[0,0,1]
	s_waitcnt lgkmcnt(2)
	v_mfma_scale_f32_32x32x64_f8f6f4 v[98:113], v[222:229], v[138:145], v[98:113], v194, v193 op_sel_hi:[0,0,0]
	ds_read_b128 v[222:225], v185 offset:38912
	ds_read_b128 v[226:229], v186 offset:38912
	v_exp_f32_e32 v0, v70
	v_exp_f32_e32 v177, v71
	v_exp_f32_e32 v179, v72
	v_exp_f32_e32 v254, v73
	v_add_f32_e32 v219, v0, v219
	v_add_f32_e32 v219, v177, v219
	v_cvt_pk_fp8_f32 v251, v0, v177
	v_add_f32_e32 v219, v179, v219
	v_add_f32_e32 v219, v254, v219
	v_cvt_pk_fp8_f32 v251, v179, v254 op_sel:[0,0,1]
	v_exp_f32_e32 v0, v74
	v_exp_f32_e32 v177, v75
	v_exp_f32_e32 v179, v76
	v_exp_f32_e32 v254, v77
	v_add_f32_e32 v219, v0, v219
	v_add_f32_e32 v219, v177, v219
	v_cvt_pk_fp8_f32 v252, v0, v177
	v_add_f32_e32 v219, v179, v219
	v_add_f32_e32 v219, v254, v219
	v_cvt_pk_fp8_f32 v252, v179, v254 op_sel:[0,0,1]
	s_waitcnt lgkmcnt(2)
	v_mfma_scale_f32_32x32x64_f8f6f4 v[114:129], v[90:97], v[130:137], v[114:129], v194, v193 op_sel_hi:[0,0,0]
	v_exp_f32_e32 v0, v78
	v_exp_f32_e32 v177, v79
	v_exp_f32_e32 v179, v80
	v_exp_f32_e32 v254, v81
	v_add_f32_e32 v219, v0, v219
	v_add_f32_e32 v219, v177, v219
	v_cvt_pk_fp8_f32 v253, v0, v177
	v_add_f32_e32 v219, v179, v219
	v_add_f32_e32 v219, v254, v219
	v_cvt_pk_fp8_f32 v253, v179, v254 op_sel:[0,0,1]
	ds_read_b128 v[90:93], v185 offset:0
	ds_read_b128 v[94:97], v186 offset:0
	ds_read_b128 v[82:85], v185 offset:2048
	ds_read_b128 v[86:89], v186 offset:2048
	ds_read_b128 v[74:77], v185 offset:4096
	ds_read_b128 v[78:81], v186 offset:4096
	ds_read_b128 v[66:69], v185 offset:6144
	ds_read_b128 v[70:73], v186 offset:6144
	s_waitcnt lgkmcnt(8)
	v_mfma_scale_f32_32x32x64_f8f6f4 v[98:113], v[222:229], v[130:137], v[98:113], v194, v193 op_sel_hi:[0,0,0]
	v_mov_b32_e32 v0, v219
	s_nop 1
	v_permlane32_swap_b32_e32 v219, v0
	v_add_f32_e32 v219, v219, v0
	v_fma_f32 v209, v209, v218, v219
	v_add_u32_e32 v176, 0x2000, v176
	v_add_u32_e32 v178, 0x20000, v178
	s_mov_b64 s[20:21], 0x1000
	v_lshl_add_u64 v[180:181], v[180:181], 0, s[20:21]
	v_max_f32_e32 v177, v114, v115
	v_max3_f32 v177, v177, v116, v117
	v_max3_f32 v177, v177, v118, v119
	v_max3_f32 v177, v177, v120, v121
	v_max3_f32 v177, v177, v122, v123
	v_max3_f32 v177, v177, v124, v125
	v_max3_f32 v177, v177, v126, v127
	v_max3_f32 v177, v177, v128, v129
	s_waitcnt lgkmcnt(6)
	v_mfma_scale_f32_32x32x64_f8f6f4 v[50:65], v[246:253], v[90:97], v[50:65], v194, v194 op_sel_hi:[0,0,0]
	v_max_f32_e32 v0, v98, v99
	v_max3_f32 v0, v0, v100, v101
	v_max3_f32 v0, v0, v102, v103
	s_waitcnt lgkmcnt(4)
	v_mfma_scale_f32_32x32x64_f8f6f4 v[34:49], v[246:253], v[82:89], v[34:49], v194, v194 op_sel_hi:[0,0,0]
	v_max3_f32 v0, v0, v104, v105
	v_max3_f32 v0, v0, v106, v107
	v_max3_f32 v0, v0, v108, v109
	s_waitcnt lgkmcnt(2)
	v_mfma_scale_f32_32x32x64_f8f6f4 v[18:33], v[246:253], v[74:81], v[18:33], v194, v194 op_sel_hi:[0,0,0]
	v_max3_f32 v0, v0, v110, v111
	v_max3_f32 v0, v0, v112, v113
	v_max_f32_e32 v177, v177, v0
	v_mov_b32_e32 v0, v177
	v_mov_b32_e32 v221, 1.0
	s_waitcnt lgkmcnt(0)
	v_mfma_scale_f32_32x32x64_f8f6f4 v[2:17], v[246:253], v[66:73], v[2:17], v194, v194 op_sel_hi:[0,0,0]
	s_waitcnt vmcnt(0)
	s_waitcnt lgkmcnt(0)
	s_barrier
	v_permlane32_swap_b32_e32 v177, v0
	v_max_f32_e32 v177, v177, v0
	v_cmp_nge_f32_e32 vcc, s90, v177
	s_cbranch_vccnz .Lmla_h0_newmax
; __device__ __forceinline__ void finishSM9(f32x16& p0, f32x16& p1, float alpha, float& l_reg, v8i32& p8) {
; #pragma unroll
;   for (int r = 0; r < 16; ++r) { p0[r] = __builtin_amdgcn_exp2f(p0[r]); p1[r] = __builtin_amdgcn_exp2f(p1[r]); }
;   float ps = 0;
; #pragma unroll
;   for (int r = 0; r < 16; ++r) ps += p0[r];
; #pragma unroll
;   for (int r = 0; r < 16; ++r) ps += p1[r];
;   { auto rr = __builtin_amdgcn_permlane32_swap(__float_as_uint(ps), __float_as_uint(ps), false, false);
;     ps = __uint_as_float(rr[0]) + __uint_as_float(rr[1]); }
;   l_reg = l_reg * alpha + ps;
; #pragma unroll
;   for (int g = 0; g < 4; ++g) {
;     int w = __builtin_amdgcn_cvt_pk_fp8_f32(p0[4 * g], p0[4 * g + 1], 0, false); p8[g] = __builtin_amdgcn_cvt_pk_fp8_f32(p0[4 * g + 2], p0[4 * g + 3], w, true);
;     int u = __builtin_amdgcn_cvt_pk_fp8_f32(p1[4 * g], p1[4 * g + 1], 0, false); p8[4 + g] = __builtin_amdgcn_cvt_pk_fp8_f32(p1[4 * g + 2], p1[4 * g + 3], u, true); }
; }
; __device__ __forceinline__ void pv8(f32x16* o, const char* Vt, const v8i32 p8, int r32, int hi) {
;   const int sw = (r32 >> 2) & 3, a0 = r32 * 64 + (((hi * 2) ^ sw) << 4), a1 = r32 * 64 + (((hi * 2 + 1) ^ sw) << 4);
; #pragma unroll
;   for (int d0 = 0; d0 < 4; ++d0) {
;     const v8i32 vf = cat8(*reinterpret_cast<const v4i32*>(Vt + d0 * 2048 + a0), *reinterpret_cast<const v4i32*>(Vt + d0 * 2048 + a1));
;     o[d0] = __builtin_amdgcn_mfma_scale_f32_32x32x64_f8f6f4(p8, vf, o[d0], 0, 0, 0, 127, 0, 127); }
; }
; __device__ __forceinline__ void qkt9(f32x16& p0, f32x16& p1, const char* Kn, const char* Kr, const v8i32* qf, const float init, int r32, int hi) {
; #pragma unroll
;   for (int r = 0; r < 16; ++r) { p0[r] = init; p1[r] = init; }
; #pragma unroll
;   for (int s = 0; s < 2; ++s) { const int c0 = s * 4 + hi * 2;
;     const v8i32 a0 = cat8(*reinterpret_cast<const v4i32*>(Kn + KN8SW(r32, c0)), *reinterpret_cast<const v4i32*>(Kn + KN8SW(r32, c0 + 1)));
;     const v8i32 a1 = cat8(*reinterpret_cast<const v4i32*>(Kn + 4096 + KN8SW(r32, c0)), *reinterpret_cast<const v4i32*>(Kn + 4096 + KN8SW(r32, c0 + 1)));
;     p0 = __builtin_amdgcn_mfma_scale_f32_32x32x64_f8f6f4(a0, qf[s], p0, 0, 0, 0, 127, 0, 124);
;     p1 = __builtin_amdgcn_mfma_scale_f32_32x32x64_f8f6f4(a1, qf[s], p1, 0, 0, 0, 127, 0, 124); }
;   { const int c0 = hi * 2;
.Lmla_h0_cont:
	ds_read_b128 v[82:85], v215 offset:51200
	ds_read_b128 v[86:89], v216 offset:51200
	ds_read_b128 v[222:225], v215 offset:55296
	ds_read_b128 v[226:229], v216 offset:55296
	s_add_i32 m0, s98, 0x0
	s_nop 0
	global_load_lds_dwordx4 v176, s[18:19]
	s_add_i32 m0, s98, 0x4000
	s_nop 0
	global_load_lds_dwordx4 v178, s[16:17]
	s_add_i32 m0, s98, 0x8000
	s_nop 0
	global_load_lds_dwordx4 v[180:181], off
	v_exp_f32_e32 v0, v114
	v_exp_f32_e32 v177, v115
	v_exp_f32_e32 v179, v116
	v_exp_f32_e32 v254, v117
	v_add_f32_e32 v219, v0, v177
	v_cvt_pk_fp8_f32 v246, v0, v177
	v_add_f32_e32 v219, v179, v219
	v_add_f32_e32 v219, v254, v219
	v_cvt_pk_fp8_f32 v246, v179, v254 op_sel:[0,0,1]
	s_waitcnt lgkmcnt(2)
	v_mfma_scale_f32_32x32x64_f8f6f4 v[82:97], v[82:89], v[146:153], v[230:245], v194, v193 op_sel_hi:[0,0,0]
	v_exp_f32_e32 v0, v118
	v_exp_f32_e32 v177, v119
	v_exp_f32_e32 v179, v120
	v_exp_f32_e32 v254, v121
	v_add_f32_e32 v219, v0, v219
	v_add_f32_e32 v219, v177, v219
	v_cvt_pk_fp8_f32 v247, v0, v177
	v_add_f32_e32 v219, v179, v219
	v_add_f32_e32 v219, v254, v219
	v_cvt_pk_fp8_f32 v247, v179, v254 op_sel:[0,0,1]
	ds_read_b128 v[114:117], v213 offset:51200
	ds_read_b128 v[118:121], v214 offset:51200
	s_waitcnt lgkmcnt(2)
	v_mfma_scale_f32_32x32x64_f8f6f4 v[66:81], v[222:229], v[146:153], v[230:245], v194, v193 op_sel_hi:[0,0,0]
	ds_read_b128 v[222:225], v213 offset:55296
	ds_read_b128 v[226:229], v214 offset:55296
	v_exp_f32_e32 v0, v122
	v_exp_f32_e32 v177, v123
	v_exp_f32_e32 v179, v124
	v_exp_f32_e32 v254, v125
	v_add_f32_e32 v219, v0, v219
	v_add_f32_e32 v219, v177, v219
	v_cvt_pk_fp8_f32 v248, v0, v177
	v_add_f32_e32 v219, v179, v219
	v_add_f32_e32 v219, v254, v219
	v_cvt_pk_fp8_f32 v248, v179, v254 op_sel:[0,0,1]
	v_exp_f32_e32 v0, v126
	v_exp_f32_e32 v177, v127
	v_exp_f32_e32 v179, v128
	v_exp_f32_e32 v254, v129
	v_add_f32_e32 v219, v0, v219
	v_add_f32_e32 v219, v177, v219
	v_cvt_pk_fp8_f32 v249, v0, v177
	v_add_f32_e32 v219, v179, v219
	v_add_f32_e32 v219, v254, v219
	v_cvt_pk_fp8_f32 v249, v179, v254 op_sel:[0,0,1]
	ds_read_b128 v[122:125], v185 offset:59392
	ds_read_b128 v[126:129], v186 offset:59392
	s_waitcnt lgkmcnt(4)
	v_mfma_scale_f32_32x32x64_f8f6f4 v[82:97], v[114:121], v[138:145], v[82:97], v194, v193 op_sel_hi:[0,0,0]
	v_exp_f32_e32 v0, v98
	v_exp_f32_e32 v177, v99
	v_exp_f32_e32 v179, v100
	v_exp_f32_e32 v254, v101
	v_add_f32_e32 v219, v0, v219
	v_add_f32_e32 v219, v177, v219
	v_cvt_pk_fp8_f32 v250, v0, v177
	v_add_f32_e32 v219, v179, v219
	v_add_f32_e32 v219, v254, v219
	v_cvt_pk_fp8_f32 v250, v179, v254 op_sel:[0,0,1]
	s_waitcnt lgkmcnt(2)
	v_mfma_scale_f32_32x32x64_f8f6f4 v[66:81], v[222:229], v[138:145], v[66:81], v194, v193 op_sel_hi:[0,0,0]
	ds_read_b128 v[222:225], v185 offset:61440
	ds_read_b128 v[226:229], v186 offset:61440
	v_exp_f32_e32 v0, v102
	v_exp_f32_e32 v177, v103
	v_exp_f32_e32 v179, v104
	v_exp_f32_e32 v254, v105
	v_add_f32_e32 v219, v0, v219
	v_add_f32_e32 v219, v177, v219
	v_cvt_pk_fp8_f32 v251, v0, v177
	v_add_f32_e32 v219, v179, v219
	v_add_f32_e32 v219, v254, v219
	v_cvt_pk_fp8_f32 v251, v179, v254 op_sel:[0,0,1]
	v_exp_f32_e32 v0, v106
	v_exp_f32_e32 v177, v107
	v_exp_f32_e32 v179, v108
	v_exp_f32_e32 v254, v109
	v_add_f32_e32 v219, v0, v219
	v_add_f32_e32 v219, v177, v219
	v_cvt_pk_fp8_f32 v252, v0, v177
	v_add_f32_e32 v219, v179, v219
	v_add_f32_e32 v219, v254, v219
	v_cvt_pk_fp8_f32 v252, v179, v254 op_sel:[0,0,1]
	s_waitcnt lgkmcnt(2)
	v_mfma_scale_f32_32x32x64_f8f6f4 v[82:97], v[122:129], v[130:137], v[82:97], v194, v193 op_sel_hi:[0,0,0]
	v_exp_f32_e32 v0, v110
	v_exp_f32_e32 v177, v111
	v_exp_f32_e32 v179, v112
	v_exp_f32_e32 v254, v113
	v_add_f32_e32 v219, v0, v219
	v_add_f32_e32 v219, v177, v219
	v_cvt_pk_fp8_f32 v253, v0, v177
	v_add_f32_e32 v219, v179, v219
	v_add_f32_e32 v219, v254, v219
	v_cvt_pk_fp8_f32 v253, v179, v254 op_sel:[0,0,1]
	ds_read_b128 v[122:125], v185 offset:8192
	ds_read_b128 v[126:129], v186 offset:8192
	ds_read_b128 v[114:117], v185 offset:10240
	ds_read_b128 v[118:121], v186 offset:10240
	ds_read_b128 v[106:109], v185 offset:12288
	ds_read_b128 v[110:113], v186 offset:12288
	ds_read_b128 v[98:101], v185 offset:14336
	ds_read_b128 v[102:105], v186 offset:14336
	s_waitcnt lgkmcnt(8)
	v_mfma_scale_f32_32x32x64_f8f6f4 v[66:81], v[222:229], v[130:137], v[66:81], v194, v193 op_sel_hi:[0,0,0]
	v_mov_b32_e32 v0, v219
	s_nop 1
	v_permlane32_swap_b32_e32 v219, v0
	v_add_f32_e32 v219, v219, v0
	v_fma_f32 v209, v209, v221, v219
	v_add_u32_e32 v176, 0x2000, v176
	v_add_u32_e32 v178, 0x20000, v178
	s_mov_b64 s[20:21], 0x1000
	v_lshl_add_u64 v[180:181], v[180:181], 0, s[20:21]
	v_max_f32_e32 v177, v82, v83
	v_max3_f32 v177, v177, v84, v85
	v_max3_f32 v177, v177, v86, v87
	v_max3_f32 v177, v177, v88, v89
	v_max3_f32 v177, v177, v90, v91
	v_max3_f32 v177, v177, v92, v93
	v_max3_f32 v177, v177, v94, v95
	v_max3_f32 v177, v177, v96, v97
	s_waitcnt lgkmcnt(6)
	v_mfma_scale_f32_32x32x64_f8f6f4 v[50:65], v[246:253], v[122:129], v[50:65], v194, v194 op_sel_hi:[0,0,0]
	v_max_f32_e32 v0, v66, v67
	v_max3_f32 v0, v0, v68, v69
	v_max3_f32 v0, v0, v70, v71
	s_waitcnt lgkmcnt(4)
	v_mfma_scale_f32_32x32x64_f8f6f4 v[34:49], v[246:253], v[114:121], v[34:49], v194, v194 op_sel_hi:[0,0,0]
	v_max3_f32 v0, v0, v72, v73
	v_max3_f32 v0, v0, v74, v75
	v_max3_f32 v0, v0, v76, v77
	s_waitcnt lgkmcnt(2)
	v_mfma_scale_f32_32x32x64_f8f6f4 v[18:33], v[246:253], v[106:113], v[18:33], v194, v194 op_sel_hi:[0,0,0]
	v_max3_f32 v0, v0, v78, v79
	v_max3_f32 v0, v0, v80, v81
	v_max_f32_e32 v177, v177, v0
	v_mov_b32_e32 v0, v177
	v_mov_b32_e32 v218, 1.0
	s_waitcnt lgkmcnt(0)
	v_mfma_scale_f32_32x32x64_f8f6f4 v[2:17], v[246:253], v[98:105], v[2:17], v194, v194 op_sel_hi:[0,0,0]
	s_waitcnt vmcnt(0)
	s_waitcnt lgkmcnt(0)
	s_barrier
	v_permlane32_swap_b32_e32 v177, v0
	v_max_f32_e32 v177, v177, v0
	v_cmp_nge_f32_e32 vcc, s90, v177
	s_cbranch_vccnz .Lmla_h1_newmax
; __device__ __forceinline__ void finishSM9(f32x16& p0, f32x16& p1, float alpha, float& l_reg, v8i32& p8) {
; #pragma unroll
;   for (int r = 0; r < 16; ++r) { p0[r] = __builtin_amdgcn_exp2f(p0[r]); p1[r] = __builtin_amdgcn_exp2f(p1[r]); }
;   float ps = 0;
; #pragma unroll
;   for (int r = 0; r < 16; ++r) ps += p0[r];
; #pragma unroll
;   for (int r = 0; r < 16; ++r) ps += p1[r];
;   { auto rr = __builtin_amdgcn_permlane32_swap(__float_as_uint(ps), __float_as_uint(ps), false, false);
;     ps = __uint_as_float(rr[0]) + __uint_as_float(rr[1]); }
;   l_reg = l_reg * alpha + ps;
; #pragma unroll
;   for (int g = 0; g < 4; ++g) {
;     int w = __builtin_amdgcn_cvt_pk_fp8_f32(p0[4 * g], p0[4 * g + 1], 0, false); p8[g] = __builtin_amdgcn_cvt_pk_fp8_f32(p0[4 * g + 2], p0[4 * g + 3], w, true);
;     int u = __builtin_amdgcn_cvt_pk_fp8_f32(p1[4 * g], p1[4 * g + 1], 0, false); p8[4 + g] = __builtin_amdgcn_cvt_pk_fp8_f32(p1[4 * g + 2], p1[4 * g + 3], u, true); }
; }
; __device__ __forceinline__ void pv8(f32x16* o, const char* Vt, const v8i32 p8, int r32, int hi) {
;   const int sw = (r32 >> 2) & 3, a0 = r32 * 64 + (((hi * 2) ^ sw) << 4), a1 = r32 * 64 + (((hi * 2 + 1) ^ sw) << 4);
; #pragma unroll
;   for (int d0 = 0; d0 < 4; ++d0) {
;     const v8i32 vf = cat8(*reinterpret_cast<const v4i32*>(Vt + d0 * 2048 + a0), *reinterpret_cast<const v4i32*>(Vt + d0 * 2048 + a1));
;     o[d0] = __builtin_amdgcn_mfma_scale_f32_32x32x64_f8f6f4(p8, vf, o[d0], 0, 0, 0, 127, 0, 127); }
; }
; __device__ __forceinline__ void qkt9(f32x16& p0, f32x16& p1, const char* Kn, const char* Kr, const v8i32* qf, const float init, int r32, int hi) {
; #pragma unroll
;   for (int r = 0; r < 16; ++r) { p0[r] = init; p1[r] = init; }
; #pragma unroll
;   for (int s = 0; s < 2; ++s) { const int c0 = s * 4 + hi * 2;
;     const v8i32 a0 = cat8(*reinterpret_cast<const v4i32*>(Kn + KN8SW(r32, c0)), *reinterpret_cast<const v4i32*>(Kn + KN8SW(r32, c0 + 1)));
;     const v8i32 a1 = cat8(*reinterpret_cast<const v4i32*>(Kn + 4096 + KN8SW(r32, c0)), *reinterpret_cast<const v4i32*>(Kn + 4096 + KN8SW(r32, c0 + 1)));
;     p0 = __builtin_amdgcn_mfma_scale_f32_32x32x64_f8f6f4(a0, qf[s], p0, 0, 0, 0, 127, 0, 124);
;     p1 = __builtin_amdgcn_mfma_scale_f32_32x32x64_f8f6f4(a1, qf[s], p1, 0, 0, 0, 127, 0, 124); }
;   { const int c0 = hi * 2;
.Lmla_h1_cont:
	ds_read_b128 v[114:117], v215 offset:16384
	ds_read_b128 v[118:121], v216 offset:16384
	ds_read_b128 v[222:225], v215 offset:20480
	ds_read_b128 v[226:229], v216 offset:20480
	s_add_i32 m0, s98, 0x2000
	s_nop 0
	global_load_lds_dwordx4 v176, s[18:19]
	s_add_i32 m0, s98, 0x6000
	s_nop 0
	global_load_lds_dwordx4 v178, s[16:17]
	s_add_i32 m0, s98, 0x9000
	s_nop 0
	global_load_lds_dwordx4 v[180:181], off
	v_exp_f32_e32 v0, v82
	v_exp_f32_e32 v177, v83
	v_exp_f32_e32 v179, v84
	v_exp_f32_e32 v254, v85
	v_add_f32_e32 v219, v0, v177
	v_cvt_pk_fp8_f32 v246, v0, v177
	v_add_f32_e32 v219, v179, v219
	v_add_f32_e32 v219, v254, v219
	v_cvt_pk_fp8_f32 v246, v179, v254 op_sel:[0,0,1]
	s_waitcnt lgkmcnt(2)
	v_mfma_scale_f32_32x32x64_f8f6f4 v[114:129], v[114:121], v[146:153], v[230:245], v194, v193 op_sel_hi:[0,0,0]
	v_exp_f32_e32 v0, v86
	v_exp_f32_e32 v177, v87
	v_exp_f32_e32 v179, v88
	v_exp_f32_e32 v254, v89
	v_add_f32_e32 v219, v0, v219
	v_add_f32_e32 v219, v177, v219
	v_cvt_pk_fp8_f32 v247, v0, v177
	v_add_f32_e32 v219, v179, v219
	v_add_f32_e32 v219, v254, v219
	v_cvt_pk_fp8_f32 v247, v179, v254 op_sel:[0,0,1]
	ds_read_b128 v[82:85], v213 offset:16384
	ds_read_b128 v[86:89], v214 offset:16384
	s_waitcnt lgkmcnt(2)
	v_mfma_scale_f32_32x32x64_f8f6f4 v[98:113], v[222:229], v[146:153], v[230:245], v194, v193 op_sel_hi:[0,0,0]
	ds_read_b128 v[222:225], v213 offset:20480
	ds_read_b128 v[226:229], v214 offset:20480
	v_exp_f32_e32 v0, v90
	v_exp_f32_e32 v177, v91
	v_exp_f32_e32 v179, v92
	v_exp_f32_e32 v254, v93
	v_add_f32_e32 v219, v0, v219
	v_add_f32_e32 v219, v177, v219
	v_cvt_pk_fp8_f32 v248, v0, v177
	v_add_f32_e32 v219, v179, v219
	v_add_f32_e32 v219, v254, v219
	v_cvt_pk_fp8_f32 v248, v179, v254 op_sel:[0,0,1]
	v_exp_f32_e32 v0, v94
	v_exp_f32_e32 v177, v95
	v_exp_f32_e32 v179, v96
	v_exp_f32_e32 v254, v97
	v_add_f32_e32 v219, v0, v219
	v_add_f32_e32 v219, v177, v219
	v_cvt_pk_fp8_f32 v249, v0, v177
	v_add_f32_e32 v219, v179, v219
	v_add_f32_e32 v219, v254, v219
	v_cvt_pk_fp8_f32 v249, v179, v254 op_sel:[0,0,1]
	ds_read_b128 v[90:93], v185 offset:32768
	ds_read_b128 v[94:97], v186 offset:32768
	s_waitcnt lgkmcnt(4)
	v_mfma_scale_f32_32x32x64_f8f6f4 v[114:129], v[82:89], v[138:145], v[114:129], v194, v193 op_sel_hi:[0,0,0]
	v_exp_f32_e32 v0, v66
	v_exp_f32_e32 v177, v67
	v_exp_f32_e32 v179, v68
	v_exp_f32_e32 v254, v69
	v_add_f32_e32 v219, v0, v219
	v_add_f32_e32 v219, v177, v219
	v_cvt_pk_fp8_f32 v250, v0, v177
	v_add_f32_e32 v219, v179, v219
	v_add_f32_e32 v219, v254, v219
	v_cvt_pk_fp8_f32 v250, v179, v254 op_sel:[0,0,1]
	s_waitcnt lgkmcnt(2)
	v_mfma_scale_f32_32x32x64_f8f6f4 v[98:113], v[222:229], v[138:145], v[98:113], v194, v193 op_sel_hi:[0,0,0]
	ds_read_b128 v[222:225], v185 offset:34816
	ds_read_b128 v[226:229], v186 offset:34816
	v_exp_f32_e32 v0, v70
	v_exp_f32_e32 v177, v71
	v_exp_f32_e32 v179, v72
	v_exp_f32_e32 v254, v73
	v_add_f32_e32 v219, v0, v219
	v_add_f32_e32 v219, v177, v219
	v_cvt_pk_fp8_f32 v251, v0, v177
	v_add_f32_e32 v219, v179, v219
	v_add_f32_e32 v219, v254, v219
	v_cvt_pk_fp8_f32 v251, v179, v254 op_sel:[0,0,1]
	v_exp_f32_e32 v0, v74
	v_exp_f32_e32 v177, v75
	v_exp_f32_e32 v179, v76
	v_exp_f32_e32 v254, v77
	v_add_f32_e32 v219, v0, v219
	v_add_f32_e32 v219, v177, v219
	v_cvt_pk_fp8_f32 v252, v0, v177
	v_add_f32_e32 v219, v179, v219
	v_add_f32_e32 v219, v254, v219
	v_cvt_pk_fp8_f32 v252, v179, v254 op_sel:[0,0,1]
	s_waitcnt lgkmcnt(2)
	v_mfma_scale_f32_32x32x64_f8f6f4 v[114:129], v[90:97], v[130:137], v[114:129], v194, v193 op_sel_hi:[0,0,0]
	v_exp_f32_e32 v0, v78
	v_exp_f32_e32 v177, v79
	v_exp_f32_e32 v179, v80
	v_exp_f32_e32 v254, v81
	v_add_f32_e32 v219, v0, v219
	v_add_f32_e32 v219, v177, v219
	v_cvt_pk_fp8_f32 v253, v0, v177
	v_add_f32_e32 v219, v179, v219
	v_add_f32_e32 v219, v254, v219
	v_cvt_pk_fp8_f32 v253, v179, v254 op_sel:[0,0,1]
	ds_read_b128 v[90:93], v185 offset:43008
	ds_read_b128 v[94:97], v186 offset:43008
	ds_read_b128 v[82:85], v185 offset:45056
	ds_read_b128 v[86:89], v186 offset:45056
	ds_read_b128 v[74:77], v185 offset:47104
	ds_read_b128 v[78:81], v186 offset:47104
	ds_read_b128 v[66:69], v185 offset:49152
	ds_read_b128 v[70:73], v186 offset:49152
	s_waitcnt lgkmcnt(8)
	v_mfma_scale_f32_32x32x64_f8f6f4 v[98:113], v[222:229], v[130:137], v[98:113], v194, v193 op_sel_hi:[0,0,0]
	v_mov_b32_e32 v0, v219
	s_nop 1
	v_permlane32_swap_b32_e32 v219, v0
	v_add_f32_e32 v219, v219, v0
	v_fma_f32 v209, v209, v218, v219
	v_add_u32_e32 v176, 0x2000, v176
	v_add_u32_e32 v178, 0x20000, v178
	s_mov_b64 s[20:21], 0x1000
	v_lshl_add_u64 v[180:181], v[180:181], 0, s[20:21]
	v_max_f32_e32 v177, v114, v115
	v_max3_f32 v177, v177, v116, v117
	v_max3_f32 v177, v177, v118, v119
	v_max3_f32 v177, v177, v120, v121
	v_max3_f32 v177, v177, v122, v123
	v_max3_f32 v177, v177, v124, v125
	v_max3_f32 v177, v177, v126, v127
	v_max3_f32 v177, v177, v128, v129
	s_waitcnt lgkmcnt(6)
	v_mfma_scale_f32_32x32x64_f8f6f4 v[50:65], v[246:253], v[90:97], v[50:65], v194, v194 op_sel_hi:[0,0,0]
	v_max_f32_e32 v0, v98, v99
	v_max3_f32 v0, v0, v100, v101
	v_max3_f32 v0, v0, v102, v103
	s_waitcnt lgkmcnt(4)
	v_mfma_scale_f32_32x32x64_f8f6f4 v[34:49], v[246:253], v[82:89], v[34:49], v194, v194 op_sel_hi:[0,0,0]
	v_max3_f32 v0, v0, v104, v105
	v_max3_f32 v0, v0, v106, v107
	v_max3_f32 v0, v0, v108, v109
	s_waitcnt lgkmcnt(2)
	v_mfma_scale_f32_32x32x64_f8f6f4 v[18:33], v[246:253], v[74:81], v[18:33], v194, v194 op_sel_hi:[0,0,0]
	v_max3_f32 v0, v0, v110, v111
	v_max3_f32 v0, v0, v112, v113
	v_max_f32_e32 v177, v177, v0
	v_mov_b32_e32 v0, v177
	v_mov_b32_e32 v221, 1.0
	s_waitcnt lgkmcnt(0)
	v_mfma_scale_f32_32x32x64_f8f6f4 v[2:17], v[246:253], v[66:73], v[2:17], v194, v194 op_sel_hi:[0,0,0]
	s_waitcnt vmcnt(0)
	s_waitcnt lgkmcnt(0)
	s_barrier
	v_permlane32_swap_b32_e32 v177, v0
	v_max_f32_e32 v177, v177, v0
	v_cmp_nge_f32_e32 vcc, s90, v177
	s_cbranch_vccnz .Lmla_h2_newmax
; __device__ __forceinline__ void finishSM9(f32x16& p0, f32x16& p1, float alpha, float& l_reg, v8i32& p8) {
; #pragma unroll
;   for (int r = 0; r < 16; ++r) { p0[r] = __builtin_amdgcn_exp2f(p0[r]); p1[r] = __builtin_amdgcn_exp2f(p1[r]); }
;   float ps = 0;
; #pragma unroll
;   for (int r = 0; r < 16; ++r) ps += p0[r];
; #pragma unroll
;   for (int r = 0; r < 16; ++r) ps += p1[r];
;   { auto rr = __builtin_amdgcn_permlane32_swap(__float_as_uint(ps), __float_as_uint(ps), false, false);
;     ps = __uint_as_float(rr[0]) + __uint_as_float(rr[1]); }
;   l_reg = l_reg * alpha + ps;
; #pragma unroll
;   for (int g = 0; g < 4; ++g) {
;     int w = __builtin_amdgcn_cvt_pk_fp8_f32(p0[4 * g], p0[4 * g + 1], 0, false); p8[g] = __builtin_amdgcn_cvt_pk_fp8_f32(p0[4 * g + 2], p0[4 * g + 3], w, true);
;     int u = __builtin_amdgcn_cvt_pk_fp8_f32(p1[4 * g], p1[4 * g + 1], 0, false); p8[4 + g] = __builtin_amdgcn_cvt_pk_fp8_f32(p1[4 * g + 2], p1[4 * g + 3], u, true); }
; }
; __device__ __forceinline__ void pv8(f32x16* o, const char* Vt, const v8i32 p8, int r32, int hi) {
;   const int sw = (r32 >> 2) & 3, a0 = r32 * 64 + (((hi * 2) ^ sw) << 4), a1 = r32 * 64 + (((hi * 2 + 1) ^ sw) << 4);
; #pragma unroll
;   for (int d0 = 0; d0 < 4; ++d0) {
;     const v8i32 vf = cat8(*reinterpret_cast<const v4i32*>(Vt + d0 * 2048 + a0), *reinterpret_cast<const v4i32*>(Vt + d0 * 2048 + a1));
;     o[d0] = __builtin_amdgcn_mfma_scale_f32_32x32x64_f8f6f4(p8, vf, o[d0], 0, 0, 0, 127, 0, 127); }
; }
; __device__ __forceinline__ void qkt9(f32x16& p0, f32x16& p1, const char* Kn, const char* Kr, const v8i32* qf, const float init, int r32, int hi) {
; #pragma unroll
;   for (int r = 0; r < 16; ++r) { p0[r] = init; p1[r] = init; }
; #pragma unroll
;   for (int s = 0; s < 2; ++s) { const int c0 = s * 4 + hi * 2;
;     const v8i32 a0 = cat8(*reinterpret_cast<const v4i32*>(Kn + KN8SW(r32, c0)), *reinterpret_cast<const v4i32*>(Kn + KN8SW(r32, c0 + 1)));
;     const v8i32 a1 = cat8(*reinterpret_cast<const v4i32*>(Kn + 4096 + KN8SW(r32, c0)), *reinterpret_cast<const v4i32*>(Kn + 4096 + KN8SW(r32, c0 + 1)));
;     p0 = __builtin_amdgcn_mfma_scale_f32_32x32x64_f8f6f4(a0, qf[s], p0, 0, 0, 0, 127, 0, 124);
;     p1 = __builtin_amdgcn_mfma_scale_f32_32x32x64_f8f6f4(a1, qf[s], p1, 0, 0, 0, 127, 0, 124); }
;   { const int c0 = hi * 2;
.Lmla_h2_cont:
	ds_read_b128 v[82:85], v215 offset:24576
	ds_read_b128 v[86:89], v216 offset:24576
	ds_read_b128 v[222:225], v215 offset:28672
	ds_read_b128 v[226:229], v216 offset:28672
	s_add_i32 m0, s98, 0xa800
	s_nop 0
	global_load_lds_dwordx4 v176, s[18:19]
	s_add_i32 m0, s98, 0xc800
	s_nop 0
	global_load_lds_dwordx4 v178, s[16:17]
	s_add_i32 m0, s98, 0xe800
	s_nop 0
	global_load_lds_dwordx4 v[180:181], off
	v_exp_f32_e32 v0, v114
	v_exp_f32_e32 v177, v115
	v_exp_f32_e32 v179, v116
	v_exp_f32_e32 v254, v117
	v_add_f32_e32 v219, v0, v177
	v_cvt_pk_fp8_f32 v246, v0, v177
	v_add_f32_e32 v219, v179, v219
	v_add_f32_e32 v219, v254, v219
	v_cvt_pk_fp8_f32 v246, v179, v254 op_sel:[0,0,1]
	s_waitcnt lgkmcnt(2)
	v_mfma_scale_f32_32x32x64_f8f6f4 v[82:97], v[82:89], v[146:153], v[230:245], v194, v193 op_sel_hi:[0,0,0]
	v_exp_f32_e32 v0, v118
	v_exp_f32_e32 v177, v119
	v_exp_f32_e32 v179, v120
	v_exp_f32_e32 v254, v121
	v_add_f32_e32 v219, v0, v219
	v_add_f32_e32 v219, v177, v219
	v_cvt_pk_fp8_f32 v247, v0, v177
	v_add_f32_e32 v219, v179, v219
	v_add_f32_e32 v219, v254, v219
	v_cvt_pk_fp8_f32 v247, v179, v254 op_sel:[0,0,1]
	ds_read_b128 v[114:117], v213 offset:24576
	ds_read_b128 v[118:121], v214 offset:24576
	s_waitcnt lgkmcnt(2)
	v_mfma_scale_f32_32x32x64_f8f6f4 v[66:81], v[222:229], v[146:153], v[230:245], v194, v193 op_sel_hi:[0,0,0]
	ds_read_b128 v[222:225], v213 offset:28672
	ds_read_b128 v[226:229], v214 offset:28672
	v_exp_f32_e32 v0, v122
	v_exp_f32_e32 v177, v123
	v_exp_f32_e32 v179, v124
	v_exp_f32_e32 v254, v125
	v_add_f32_e32 v219, v0, v219
	v_add_f32_e32 v219, v177, v219
	v_cvt_pk_fp8_f32 v248, v0, v177
	v_add_f32_e32 v219, v179, v219
	v_add_f32_e32 v219, v254, v219
	v_cvt_pk_fp8_f32 v248, v179, v254 op_sel:[0,0,1]
	v_exp_f32_e32 v0, v126
	v_exp_f32_e32 v177, v127
	v_exp_f32_e32 v179, v128
	v_exp_f32_e32 v254, v129
	v_add_f32_e32 v219, v0, v219
	v_add_f32_e32 v219, v177, v219
	v_cvt_pk_fp8_f32 v249, v0, v177
	v_add_f32_e32 v219, v179, v219
	v_add_f32_e32 v219, v254, v219
	v_cvt_pk_fp8_f32 v249, v179, v254 op_sel:[0,0,1]
	ds_read_b128 v[122:125], v185 offset:36864
	ds_read_b128 v[126:129], v186 offset:36864
	s_waitcnt lgkmcnt(4)
	v_mfma_scale_f32_32x32x64_f8f6f4 v[82:97], v[114:121], v[138:145], v[82:97], v194, v193 op_sel_hi:[0,0,0]
	v_exp_f32_e32 v0, v98
	v_exp_f32_e32 v177, v99
	v_exp_f32_e32 v179, v100
	v_exp_f32_e32 v254, v101
	v_add_f32_e32 v219, v0, v219
	v_add_f32_e32 v219, v177, v219
	v_cvt_pk_fp8_f32 v250, v0, v177
	v_add_f32_e32 v219, v179, v219
	v_add_f32_e32 v219, v254, v219
	v_cvt_pk_fp8_f32 v250, v179, v254 op_sel:[0,0,1]
	s_waitcnt lgkmcnt(2)
	v_mfma_scale_f32_32x32x64_f8f6f4 v[66:81], v[222:229], v[138:145], v[66:81], v194, v193 op_sel_hi:[0,0,0]
	ds_read_b128 v[222:225], v185 offset:38912
	ds_read_b128 v[226:229], v186 offset:38912
	v_exp_f32_e32 v0, v102
	v_exp_f32_e32 v177, v103
	v_exp_f32_e32 v179, v104
	v_exp_f32_e32 v254, v105
	v_add_f32_e32 v219, v0, v219
	v_add_f32_e32 v219, v177, v219
	v_cvt_pk_fp8_f32 v251, v0, v177
	v_add_f32_e32 v219, v179, v219
	v_add_f32_e32 v219, v254, v219
	v_cvt_pk_fp8_f32 v251, v179, v254 op_sel:[0,0,1]
	v_exp_f32_e32 v0, v106
	v_exp_f32_e32 v177, v107
	v_exp_f32_e32 v179, v108
	v_exp_f32_e32 v254, v109
	v_add_f32_e32 v219, v0, v219
	v_add_f32_e32 v219, v177, v219
	v_cvt_pk_fp8_f32 v252, v0, v177
	v_add_f32_e32 v219, v179, v219
	v_add_f32_e32 v219, v254, v219
	v_cvt_pk_fp8_f32 v252, v179, v254 op_sel:[0,0,1]
	s_waitcnt lgkmcnt(2)
	v_mfma_scale_f32_32x32x64_f8f6f4 v[82:97], v[122:129], v[130:137], v[82:97], v194, v193 op_sel_hi:[0,0,0]
	v_exp_f32_e32 v0, v110
	v_exp_f32_e32 v177, v111
	v_exp_f32_e32 v179, v112
	v_exp_f32_e32 v254, v113
	v_add_f32_e32 v219, v0, v219
	v_add_f32_e32 v219, v177, v219
	v_cvt_pk_fp8_f32 v253, v0, v177
	v_add_f32_e32 v219, v179, v219
	v_add_f32_e32 v219, v254, v219
	v_cvt_pk_fp8_f32 v253, v179, v254 op_sel:[0,0,1]
	ds_read_b128 v[122:125], v185 offset:0
	ds_read_b128 v[126:129], v186 offset:0
	ds_read_b128 v[114:117], v185 offset:2048
	ds_read_b128 v[118:121], v186 offset:2048
	ds_read_b128 v[106:109], v185 offset:4096
	ds_read_b128 v[110:113], v186 offset:4096
	ds_read_b128 v[98:101], v185 offset:6144
	ds_read_b128 v[102:105], v186 offset:6144
	s_waitcnt lgkmcnt(8)
	v_mfma_scale_f32_32x32x64_f8f6f4 v[66:81], v[222:229], v[130:137], v[66:81], v194, v193 op_sel_hi:[0,0,0]
	v_mov_b32_e32 v0, v219
	s_nop 1
	v_permlane32_swap_b32_e32 v219, v0
	v_add_f32_e32 v219, v219, v0
	v_fma_f32 v209, v209, v221, v219
	v_add_u32_e32 v176, 0x2000, v176
	v_add_u32_e32 v178, 0x20000, v178
	s_mov_b64 s[20:21], 0x1000
	v_lshl_add_u64 v[180:181], v[180:181], 0, s[20:21]
	v_max_f32_e32 v177, v82, v83
	v_max3_f32 v177, v177, v84, v85
	v_max3_f32 v177, v177, v86, v87
	v_max3_f32 v177, v177, v88, v89
	v_max3_f32 v177, v177, v90, v91
	v_max3_f32 v177, v177, v92, v93
	v_max3_f32 v177, v177, v94, v95
	v_max3_f32 v177, v177, v96, v97
	s_waitcnt lgkmcnt(6)
	v_mfma_scale_f32_32x32x64_f8f6f4 v[50:65], v[246:253], v[122:129], v[50:65], v194, v194 op_sel_hi:[0,0,0]
	v_max_f32_e32 v0, v66, v67
	v_max3_f32 v0, v0, v68, v69
	v_max3_f32 v0, v0, v70, v71
	s_waitcnt lgkmcnt(4)
	v_mfma_scale_f32_32x32x64_f8f6f4 v[34:49], v[246:253], v[114:121], v[34:49], v194, v194 op_sel_hi:[0,0,0]
	v_max3_f32 v0, v0, v72, v73
	v_max3_f32 v0, v0, v74, v75
	v_max3_f32 v0, v0, v76, v77
	s_waitcnt lgkmcnt(2)
	v_mfma_scale_f32_32x32x64_f8f6f4 v[18:33], v[246:253], v[106:113], v[18:33], v194, v194 op_sel_hi:[0,0,0]
	v_max3_f32 v0, v0, v78, v79
	v_max3_f32 v0, v0, v80, v81
	v_max_f32_e32 v177, v177, v0
	v_mov_b32_e32 v0, v177
	v_mov_b32_e32 v218, 1.0
	s_waitcnt lgkmcnt(0)
	v_mfma_scale_f32_32x32x64_f8f6f4 v[2:17], v[246:253], v[98:105], v[2:17], v194, v194 op_sel_hi:[0,0,0]
	s_waitcnt vmcnt(0)
	s_waitcnt lgkmcnt(0)
	s_barrier
	v_permlane32_swap_b32_e32 v177, v0
	v_max_f32_e32 v177, v177, v0
	v_cmp_nge_f32_e32 vcc, s90, v177
	s_cbranch_vccnz .Lmla_h3_newmax
; __device__ __forceinline__ void finishSM9(f32x16& p0, f32x16& p1, float alpha, float& l_reg, v8i32& p8) {
; #pragma unroll
;   for (int r = 0; r < 16; ++r) { p0[r] = __builtin_amdgcn_exp2f(p0[r]); p1[r] = __builtin_amdgcn_exp2f(p1[r]); }
;   float ps = 0;
; #pragma unroll
;   for (int r = 0; r < 16; ++r) ps += p0[r];
; #pragma unroll
;   for (int r = 0; r < 16; ++r) ps += p1[r];
;   { auto rr = __builtin_amdgcn_permlane32_swap(__float_as_uint(ps), __float_as_uint(ps), false, false);
;     ps = __uint_as_float(rr[0]) + __uint_as_float(rr[1]); }
;   l_reg = l_reg * alpha + ps;
; #pragma unroll
;   for (int g = 0; g < 4; ++g) {
;     int w = __builtin_amdgcn_cvt_pk_fp8_f32(p0[4 * g], p0[4 * g + 1], 0, false); p8[g] = __builtin_amdgcn_cvt_pk_fp8_f32(p0[4 * g + 2], p0[4 * g + 3], w, true);
;     int u = __builtin_amdgcn_cvt_pk_fp8_f32(p1[4 * g], p1[4 * g + 1], 0, false); p8[4 + g] = __builtin_amdgcn_cvt_pk_fp8_f32(p1[4 * g + 2], p1[4 * g + 3], u, true); }
; }
; __device__ __forceinline__ void pv8(f32x16* o, const char* Vt, const v8i32 p8, int r32, int hi) {
;   const int sw = (r32 >> 2) & 3, a0 = r32 * 64 + (((hi * 2) ^ sw) << 4), a1 = r32 * 64 + (((hi * 2 + 1) ^ sw) << 4);
; #pragma unroll
;   for (int d0 = 0; d0 < 4; ++d0) {
;     const v8i32 vf = cat8(*reinterpret_cast<const v4i32*>(Vt + d0 * 2048 + a0), *reinterpret_cast<const v4i32*>(Vt + d0 * 2048 + a1));
;     o[d0] = __builtin_amdgcn_mfma_scale_f32_32x32x64_f8f6f4(p8, vf, o[d0], 0, 0, 0, 127, 0, 127); }
; }
; __device__ __forceinline__ void qkt9(f32x16& p0, f32x16& p1, const char* Kn, const char* Kr, const v8i32* qf, const float init, int r32, int hi) {
; #pragma unroll
;   for (int r = 0; r < 16; ++r) { p0[r] = init; p1[r] = init; }
; #pragma unroll
;   for (int s = 0; s < 2; ++s) { const int c0 = s * 4 + hi * 2;
;     const v8i32 a0 = cat8(*reinterpret_cast<const v4i32*>(Kn + KN8SW(r32, c0)), *reinterpret_cast<const v4i32*>(Kn + KN8SW(r32, c0 + 1)));
;     const v8i32 a1 = cat8(*reinterpret_cast<const v4i32*>(Kn + 4096 + KN8SW(r32, c0)), *reinterpret_cast<const v4i32*>(Kn + 4096 + KN8SW(r32, c0 + 1)));
;     p0 = __builtin_amdgcn_mfma_scale_f32_32x32x64_f8f6f4(a0, qf[s], p0, 0, 0, 0, 127, 0, 124);
;     p1 = __builtin_amdgcn_mfma_scale_f32_32x32x64_f8f6f4(a1, qf[s], p1, 0, 0, 0, 127, 0, 124); }
;   { const int c0 = hi * 2;
.Lmla_h3_cont:
	ds_read_b128 v[114:117], v215 offset:51200
	ds_read_b128 v[118:121], v216 offset:51200
	ds_read_b128 v[222:225], v215 offset:55296
	ds_read_b128 v[226:229], v216 offset:55296
	s_add_i32 m0, s98, 0x0
	s_nop 0
	global_load_lds_dwordx4 v176, s[18:19]
	s_add_i32 m0, s98, 0x4000
	s_nop 0
	global_load_lds_dwordx4 v178, s[16:17]
	s_add_i32 m0, s98, 0x8000
	s_nop 0
	global_load_lds_dwordx4 v[180:181], off
	v_exp_f32_e32 v0, v82
	v_exp_f32_e32 v177, v83
	v_exp_f32_e32 v179, v84
	v_exp_f32_e32 v254, v85
	v_add_f32_e32 v219, v0, v177
	v_cvt_pk_fp8_f32 v246, v0, v177
	v_add_f32_e32 v219, v179, v219
	v_add_f32_e32 v219, v254, v219
	v_cvt_pk_fp8_f32 v246, v179, v254 op_sel:[0,0,1]
	s_waitcnt lgkmcnt(2)
	v_mfma_scale_f32_32x32x64_f8f6f4 v[114:129], v[114:121], v[146:153], v[230:245], v194, v193 op_sel_hi:[0,0,0]
	v_exp_f32_e32 v0, v86
	v_exp_f32_e32 v177, v87
	v_exp_f32_e32 v179, v88
	v_exp_f32_e32 v254, v89
	v_add_f32_e32 v219, v0, v219
	v_add_f32_e32 v219, v177, v219
	v_cvt_pk_fp8_f32 v247, v0, v177
	v_add_f32_e32 v219, v179, v219
	v_add_f32_e32 v219, v254, v219
	v_cvt_pk_fp8_f32 v247, v179, v254 op_sel:[0,0,1]
	ds_read_b128 v[82:85], v213 offset:51200
	ds_read_b128 v[86:89], v214 offset:51200
	s_waitcnt lgkmcnt(2)
	v_mfma_scale_f32_32x32x64_f8f6f4 v[98:113], v[222:229], v[146:153], v[230:245], v194, v193 op_sel_hi:[0,0,0]
	ds_read_b128 v[222:225], v213 offset:55296
	ds_read_b128 v[226:229], v214 offset:55296
	v_exp_f32_e32 v0, v90
	v_exp_f32_e32 v177, v91
	v_exp_f32_e32 v179, v92
	v_exp_f32_e32 v254, v93
	v_add_f32_e32 v219, v0, v219
	v_add_f32_e32 v219, v177, v219
	v_cvt_pk_fp8_f32 v248, v0, v177
	v_add_f32_e32 v219, v179, v219
	v_add_f32_e32 v219, v254, v219
	v_cvt_pk_fp8_f32 v248, v179, v254 op_sel:[0,0,1]
	v_exp_f32_e32 v0, v94
	v_exp_f32_e32 v177, v95
	v_exp_f32_e32 v179, v96
	v_exp_f32_e32 v254, v97
	v_add_f32_e32 v219, v0, v219
	v_add_f32_e32 v219, v177, v219
	v_cvt_pk_fp8_f32 v249, v0, v177
	v_add_f32_e32 v219, v179, v219
	v_add_f32_e32 v219, v254, v219
	v_cvt_pk_fp8_f32 v249, v179, v254 op_sel:[0,0,1]
	ds_read_b128 v[90:93], v185 offset:59392
	ds_read_b128 v[94:97], v186 offset:59392
	s_waitcnt lgkmcnt(4)
	v_mfma_scale_f32_32x32x64_f8f6f4 v[114:129], v[82:89], v[138:145], v[114:129], v194, v193 op_sel_hi:[0,0,0]
	v_exp_f32_e32 v0, v66
	v_exp_f32_e32 v177, v67
	v_exp_f32_e32 v179, v68
	v_exp_f32_e32 v254, v69
	v_add_f32_e32 v219, v0, v219
	v_add_f32_e32 v219, v177, v219
	v_cvt_pk_fp8_f32 v250, v0, v177
	v_add_f32_e32 v219, v179, v219
	v_add_f32_e32 v219, v254, v219
	v_cvt_pk_fp8_f32 v250, v179, v254 op_sel:[0,0,1]
	s_waitcnt lgkmcnt(2)
	v_mfma_scale_f32_32x32x64_f8f6f4 v[98:113], v[222:229], v[138:145], v[98:113], v194, v193 op_sel_hi:[0,0,0]
	ds_read_b128 v[222:225], v185 offset:61440
	ds_read_b128 v[226:229], v186 offset:61440
	v_exp_f32_e32 v0, v70
	v_exp_f32_e32 v177, v71
	v_exp_f32_e32 v179, v72
	v_exp_f32_e32 v254, v73
	v_add_f32_e32 v219, v0, v219
	v_add_f32_e32 v219, v177, v219
	v_cvt_pk_fp8_f32 v251, v0, v177
	v_add_f32_e32 v219, v179, v219
	v_add_f32_e32 v219, v254, v219
	v_cvt_pk_fp8_f32 v251, v179, v254 op_sel:[0,0,1]
	v_exp_f32_e32 v0, v74
	v_exp_f32_e32 v177, v75
	v_exp_f32_e32 v179, v76
	v_exp_f32_e32 v254, v77
	v_add_f32_e32 v219, v0, v219
	v_add_f32_e32 v219, v177, v219
	v_cvt_pk_fp8_f32 v252, v0, v177
	v_add_f32_e32 v219, v179, v219
	v_add_f32_e32 v219, v254, v219
	v_cvt_pk_fp8_f32 v252, v179, v254 op_sel:[0,0,1]
	s_waitcnt lgkmcnt(2)
	v_mfma_scale_f32_32x32x64_f8f6f4 v[114:129], v[90:97], v[130:137], v[114:129], v194, v193 op_sel_hi:[0,0,0]
	v_exp_f32_e32 v0, v78
	v_exp_f32_e32 v177, v79
	v_exp_f32_e32 v179, v80
	v_exp_f32_e32 v254, v81
	v_add_f32_e32 v219, v0, v219
	v_add_f32_e32 v219, v177, v219
	v_cvt_pk_fp8_f32 v253, v0, v177
	v_add_f32_e32 v219, v179, v219
	v_add_f32_e32 v219, v254, v219
	v_cvt_pk_fp8_f32 v253, v179, v254 op_sel:[0,0,1]
	ds_read_b128 v[90:93], v185 offset:8192
	ds_read_b128 v[94:97], v186 offset:8192
	ds_read_b128 v[82:85], v185 offset:10240
	ds_read_b128 v[86:89], v186 offset:10240
	ds_read_b128 v[74:77], v185 offset:12288
	ds_read_b128 v[78:81], v186 offset:12288
	ds_read_b128 v[66:69], v185 offset:14336
	ds_read_b128 v[70:73], v186 offset:14336
	s_waitcnt lgkmcnt(8)
	v_mfma_scale_f32_32x32x64_f8f6f4 v[98:113], v[222:229], v[130:137], v[98:113], v194, v193 op_sel_hi:[0,0,0]
	v_mov_b32_e32 v0, v219
	s_nop 1
	v_permlane32_swap_b32_e32 v219, v0
	v_add_f32_e32 v219, v219, v0
	v_fma_f32 v209, v209, v218, v219
	v_add_u32_e32 v176, 0x2000, v176
	v_add_u32_e32 v178, 0x20000, v178
	s_mov_b64 s[20:21], 0x1000
	v_lshl_add_u64 v[180:181], v[180:181], 0, s[20:21]
	v_max_f32_e32 v177, v114, v115
	v_max3_f32 v177, v177, v116, v117
	v_max3_f32 v177, v177, v118, v119
	v_max3_f32 v177, v177, v120, v121
	v_max3_f32 v177, v177, v122, v123
	v_max3_f32 v177, v177, v124, v125
	v_max3_f32 v177, v177, v126, v127
	v_max3_f32 v177, v177, v128, v129
	s_waitcnt lgkmcnt(6)
	v_mfma_scale_f32_32x32x64_f8f6f4 v[50:65], v[246:253], v[90:97], v[50:65], v194, v194 op_sel_hi:[0,0,0]
	v_max_f32_e32 v0, v98, v99
	v_max3_f32 v0, v0, v100, v101
	v_max3_f32 v0, v0, v102, v103
	s_waitcnt lgkmcnt(4)
	v_mfma_scale_f32_32x32x64_f8f6f4 v[34:49], v[246:253], v[82:89], v[34:49], v194, v194 op_sel_hi:[0,0,0]
	v_max3_f32 v0, v0, v104, v105
	v_max3_f32 v0, v0, v106, v107
	v_max3_f32 v0, v0, v108, v109
	s_waitcnt lgkmcnt(2)
	v_mfma_scale_f32_32x32x64_f8f6f4 v[18:33], v[246:253], v[74:81], v[18:33], v194, v194 op_sel_hi:[0,0,0]
	v_max3_f32 v0, v0, v110, v111
	v_max3_f32 v0, v0, v112, v113
	v_max_f32_e32 v177, v177, v0
	v_mov_b32_e32 v0, v177
	v_mov_b32_e32 v221, 1.0
	s_waitcnt lgkmcnt(0)
	v_mfma_scale_f32_32x32x64_f8f6f4 v[2:17], v[246:253], v[66:73], v[2:17], v194, v194 op_sel_hi:[0,0,0]
	s_waitcnt vmcnt(0)
	s_waitcnt lgkmcnt(0)
	s_barrier
	v_permlane32_swap_b32_e32 v177, v0
	v_max_f32_e32 v177, v177, v0
	v_cmp_nge_f32_e32 vcc, s90, v177
	s_cbranch_vccnz .Lmla_h4_newmax
; __device__ __forceinline__ void finishSM9(f32x16& p0, f32x16& p1, float alpha, float& l_reg, v8i32& p8) {
; #pragma unroll
;   for (int r = 0; r < 16; ++r) { p0[r] = __builtin_amdgcn_exp2f(p0[r]); p1[r] = __builtin_amdgcn_exp2f(p1[r]); }
;   float ps = 0;
; #pragma unroll
;   for (int r = 0; r < 16; ++r) ps += p0[r];
; #pragma unroll
;   for (int r = 0; r < 16; ++r) ps += p1[r];
;   { auto rr = __builtin_amdgcn_permlane32_swap(__float_as_uint(ps), __float_as_uint(ps), false, false);
;     ps = __uint_as_float(rr[0]) + __uint_as_float(rr[1]); }
;   l_reg = l_reg * alpha + ps;
; #pragma unroll
;   for (int g = 0; g < 4; ++g) {
;     int w = __builtin_amdgcn_cvt_pk_fp8_f32(p0[4 * g], p0[4 * g + 1], 0, false); p8[g] = __builtin_amdgcn_cvt_pk_fp8_f32(p0[4 * g + 2], p0[4 * g + 3], w, true);
;     int u = __builtin_amdgcn_cvt_pk_fp8_f32(p1[4 * g], p1[4 * g + 1], 0, false); p8[4 + g] = __builtin_amdgcn_cvt_pk_fp8_f32(p1[4 * g + 2], p1[4 * g + 3], u, true); }
; }
; __device__ __forceinline__ void pv8(f32x16* o, const char* Vt, const v8i32 p8, int r32, int hi) {
;   const int sw = (r32 >> 2) & 3, a0 = r32 * 64 + (((hi * 2) ^ sw) << 4), a1 = r32 * 64 + (((hi * 2 + 1) ^ sw) << 4);
; #pragma unroll
;   for (int d0 = 0; d0 < 4; ++d0) {
;     const v8i32 vf = cat8(*reinterpret_cast<const v4i32*>(Vt + d0 * 2048 + a0), *reinterpret_cast<const v4i32*>(Vt + d0 * 2048 + a1));
;     o[d0] = __builtin_amdgcn_mfma_scale_f32_32x32x64_f8f6f4(p8, vf, o[d0], 0, 0, 0, 127, 0, 127); }
; }
; __device__ __forceinline__ void qkt9(f32x16& p0, f32x16& p1, const char* Kn, const char* Kr, const v8i32* qf, const float init, int r32, int hi) {
; #pragma unroll
;   for (int r = 0; r < 16; ++r) { p0[r] = init; p1[r] = init; }
; #pragma unroll
;   for (int s = 0; s < 2; ++s) { const int c0 = s * 4 + hi * 2;
;     const v8i32 a0 = cat8(*reinterpret_cast<const v4i32*>(Kn + KN8SW(r32, c0)), *reinterpret_cast<const v4i32*>(Kn + KN8SW(r32, c0 + 1)));
;     const v8i32 a1 = cat8(*reinterpret_cast<const v4i32*>(Kn + 4096 + KN8SW(r32, c0)), *reinterpret_cast<const v4i32*>(Kn + 4096 + KN8SW(r32, c0 + 1)));
;     p0 = __builtin_amdgcn_mfma_scale_f32_32x32x64_f8f6f4(a0, qf[s], p0, 0, 0, 0, 127, 0, 124);
;     p1 = __builtin_amdgcn_mfma_scale_f32_32x32x64_f8f6f4(a1, qf[s], p1, 0, 0, 0, 127, 0, 124); }
;   { const int c0 = hi * 2;
.Lmla_h4_cont:
	ds_read_b128 v[82:85], v215 offset:16384
	ds_read_b128 v[86:89], v216 offset:16384
	ds_read_b128 v[222:225], v215 offset:20480
	ds_read_b128 v[226:229], v216 offset:20480
	s_add_i32 m0, s98, 0x2000
	s_nop 0
	global_load_lds_dwordx4 v176, s[18:19]
	s_add_i32 m0, s98, 0x6000
	s_nop 0
	global_load_lds_dwordx4 v178, s[16:17]
	s_add_i32 m0, s98, 0x9000
	s_nop 0
	global_load_lds_dwordx4 v[180:181], off
	v_exp_f32_e32 v0, v114
	v_exp_f32_e32 v177, v115
	v_exp_f32_e32 v179, v116
	v_exp_f32_e32 v254, v117
	v_add_f32_e32 v219, v0, v177
	v_cvt_pk_fp8_f32 v246, v0, v177
	v_add_f32_e32 v219, v179, v219
	v_add_f32_e32 v219, v254, v219
	v_cvt_pk_fp8_f32 v246, v179, v254 op_sel:[0,0,1]
	s_waitcnt lgkmcnt(2)
	v_mfma_scale_f32_32x32x64_f8f6f4 v[82:97], v[82:89], v[146:153], v[230:245], v194, v193 op_sel_hi:[0,0,0]
	v_exp_f32_e32 v0, v118
	v_exp_f32_e32 v177, v119
	v_exp_f32_e32 v179, v120
	v_exp_f32_e32 v254, v121
	v_add_f32_e32 v219, v0, v219
	v_add_f32_e32 v219, v177, v219
	v_cvt_pk_fp8_f32 v247, v0, v177
	v_add_f32_e32 v219, v179, v219
	v_add_f32_e32 v219, v254, v219
	v_cvt_pk_fp8_f32 v247, v179, v254 op_sel:[0,0,1]
	ds_read_b128 v[114:117], v213 offset:16384
	ds_read_b128 v[118:121], v214 offset:16384
	s_waitcnt lgkmcnt(2)
	v_mfma_scale_f32_32x32x64_f8f6f4 v[66:81], v[222:229], v[146:153], v[230:245], v194, v193 op_sel_hi:[0,0,0]
	ds_read_b128 v[222:225], v213 offset:20480
	ds_read_b128 v[226:229], v214 offset:20480
	v_exp_f32_e32 v0, v122
	v_exp_f32_e32 v177, v123
	v_exp_f32_e32 v179, v124
	v_exp_f32_e32 v254, v125
	v_add_f32_e32 v219, v0, v219
	v_add_f32_e32 v219, v177, v219
	v_cvt_pk_fp8_f32 v248, v0, v177
	v_add_f32_e32 v219, v179, v219
	v_add_f32_e32 v219, v254, v219
	v_cvt_pk_fp8_f32 v248, v179, v254 op_sel:[0,0,1]
	v_exp_f32_e32 v0, v126
	v_exp_f32_e32 v177, v127
	v_exp_f32_e32 v179, v128
	v_exp_f32_e32 v254, v129
	v_add_f32_e32 v219, v0, v219
	v_add_f32_e32 v219, v177, v219
	v_cvt_pk_fp8_f32 v249, v0, v177
	v_add_f32_e32 v219, v179, v219
	v_add_f32_e32 v219, v254, v219
	v_cvt_pk_fp8_f32 v249, v179, v254 op_sel:[0,0,1]
	ds_read_b128 v[122:125], v185 offset:32768
	ds_read_b128 v[126:129], v186 offset:32768
	s_waitcnt lgkmcnt(4)
	v_mfma_scale_f32_32x32x64_f8f6f4 v[82:97], v[114:121], v[138:145], v[82:97], v194, v193 op_sel_hi:[0,0,0]
	v_exp_f32_e32 v0, v98
	v_exp_f32_e32 v177, v99
	v_exp_f32_e32 v179, v100
	v_exp_f32_e32 v254, v101
	v_add_f32_e32 v219, v0, v219
	v_add_f32_e32 v219, v177, v219
	v_cvt_pk_fp8_f32 v250, v0, v177
	v_add_f32_e32 v219, v179, v219
	v_add_f32_e32 v219, v254, v219
	v_cvt_pk_fp8_f32 v250, v179, v254 op_sel:[0,0,1]
	s_waitcnt lgkmcnt(2)
	v_mfma_scale_f32_32x32x64_f8f6f4 v[66:81], v[222:229], v[138:145], v[66:81], v194, v193 op_sel_hi:[0,0,0]
	ds_read_b128 v[222:225], v185 offset:34816
	ds_read_b128 v[226:229], v186 offset:34816
	v_exp_f32_e32 v0, v102
	v_exp_f32_e32 v177, v103
	v_exp_f32_e32 v179, v104
	v_exp_f32_e32 v254, v105
	v_add_f32_e32 v219, v0, v219
	v_add_f32_e32 v219, v177, v219
	v_cvt_pk_fp8_f32 v251, v0, v177
	v_add_f32_e32 v219, v179, v219
	v_add_f32_e32 v219, v254, v219
	v_cvt_pk_fp8_f32 v251, v179, v254 op_sel:[0,0,1]
	v_exp_f32_e32 v0, v106
	v_exp_f32_e32 v177, v107
	v_exp_f32_e32 v179, v108
	v_exp_f32_e32 v254, v109
	v_add_f32_e32 v219, v0, v219
	v_add_f32_e32 v219, v177, v219
	v_cvt_pk_fp8_f32 v252, v0, v177
	v_add_f32_e32 v219, v179, v219
	v_add_f32_e32 v219, v254, v219
	v_cvt_pk_fp8_f32 v252, v179, v254 op_sel:[0,0,1]
	s_waitcnt lgkmcnt(2)
	v_mfma_scale_f32_32x32x64_f8f6f4 v[82:97], v[122:129], v[130:137], v[82:97], v194, v193 op_sel_hi:[0,0,0]
	v_exp_f32_e32 v0, v110
	v_exp_f32_e32 v177, v111
	v_exp_f32_e32 v179, v112
	v_exp_f32_e32 v254, v113
	v_add_f32_e32 v219, v0, v219
	v_add_f32_e32 v219, v177, v219
	v_cvt_pk_fp8_f32 v253, v0, v177
	v_add_f32_e32 v219, v179, v219
	v_add_f32_e32 v219, v254, v219
	v_cvt_pk_fp8_f32 v253, v179, v254 op_sel:[0,0,1]
	ds_read_b128 v[122:125], v185 offset:43008
	ds_read_b128 v[126:129], v186 offset:43008
	ds_read_b128 v[114:117], v185 offset:45056
	ds_read_b128 v[118:121], v186 offset:45056
	ds_read_b128 v[106:109], v185 offset:47104
	ds_read_b128 v[110:113], v186 offset:47104
	ds_read_b128 v[98:101], v185 offset:49152
	ds_read_b128 v[102:105], v186 offset:49152
	s_waitcnt lgkmcnt(8)
	v_mfma_scale_f32_32x32x64_f8f6f4 v[66:81], v[222:229], v[130:137], v[66:81], v194, v193 op_sel_hi:[0,0,0]
	v_mov_b32_e32 v0, v219
	s_nop 1
	v_permlane32_swap_b32_e32 v219, v0
	v_add_f32_e32 v219, v219, v0
	v_fma_f32 v209, v209, v221, v219
	v_add_u32_e32 v176, 0x2000, v176
	v_add_u32_e32 v178, 0x20000, v178
	s_mov_b64 s[20:21], 0x1000
	v_lshl_add_u64 v[180:181], v[180:181], 0, s[20:21]
	v_max_f32_e32 v177, v82, v83
	v_max3_f32 v177, v177, v84, v85
	v_max3_f32 v177, v177, v86, v87
	v_max3_f32 v177, v177, v88, v89
	v_max3_f32 v177, v177, v90, v91
	v_max3_f32 v177, v177, v92, v93
	v_max3_f32 v177, v177, v94, v95
	v_max3_f32 v177, v177, v96, v97
	s_waitcnt lgkmcnt(6)
	v_mfma_scale_f32_32x32x64_f8f6f4 v[50:65], v[246:253], v[122:129], v[50:65], v194, v194 op_sel_hi:[0,0,0]
	v_max_f32_e32 v0, v66, v67
	v_max3_f32 v0, v0, v68, v69
	v_max3_f32 v0, v0, v70, v71
	s_waitcnt lgkmcnt(4)
	v_mfma_scale_f32_32x32x64_f8f6f4 v[34:49], v[246:253], v[114:121], v[34:49], v194, v194 op_sel_hi:[0,0,0]
	v_max3_f32 v0, v0, v72, v73
	v_max3_f32 v0, v0, v74, v75
	v_max3_f32 v0, v0, v76, v77
	s_waitcnt lgkmcnt(2)
	v_mfma_scale_f32_32x32x64_f8f6f4 v[18:33], v[246:253], v[106:113], v[18:33], v194, v194 op_sel_hi:[0,0,0]
	v_max3_f32 v0, v0, v78, v79
	v_max3_f32 v0, v0, v80, v81
	v_max_f32_e32 v177, v177, v0
	v_mov_b32_e32 v0, v177
	v_mov_b32_e32 v218, 1.0
	s_waitcnt lgkmcnt(0)
	v_mfma_scale_f32_32x32x64_f8f6f4 v[2:17], v[246:253], v[98:105], v[2:17], v194, v194 op_sel_hi:[0,0,0]
	s_waitcnt vmcnt(0)
	s_waitcnt lgkmcnt(0)
	s_barrier
	v_permlane32_swap_b32_e32 v177, v0
	v_max_f32_e32 v177, v177, v0
	v_cmp_nge_f32_e32 vcc, s90, v177
	s_cbranch_vccnz .Lmla_h5_newmax
; __device__ __forceinline__ void finishSM9(f32x16& p0, f32x16& p1, float alpha, float& l_reg, v8i32& p8) {
; #pragma unroll
;   for (int r = 0; r < 16; ++r) { p0[r] = __builtin_amdgcn_exp2f(p0[r]); p1[r] = __builtin_amdgcn_exp2f(p1[r]); }
;   float ps = 0;
; #pragma unroll
;   for (int r = 0; r < 16; ++r) ps += p0[r];
; #pragma unroll
;   for (int r = 0; r < 16; ++r) ps += p1[r];
;   { auto rr = __builtin_amdgcn_permlane32_swap(__float_as_uint(ps), __float_as_uint(ps), false, false);
;     ps = __uint_as_float(rr[0]) + __uint_as_float(rr[1]); }
;   l_reg = l_reg * alpha + ps;
; #pragma unroll
;   for (int g = 0; g < 4; ++g) {
;     int w = __builtin_amdgcn_cvt_pk_fp8_f32(p0[4 * g], p0[4 * g + 1], 0, false); p8[g] = __builtin_amdgcn_cvt_pk_fp8_f32(p0[4 * g + 2], p0[4 * g + 3], w, true);
;     int u = __builtin_amdgcn_cvt_pk_fp8_f32(p1[4 * g], p1[4 * g + 1], 0, false); p8[4 + g] = __builtin_amdgcn_cvt_pk_fp8_f32(p1[4 * g + 2], p1[4 * g + 3], u, true); }
; }
; __device__ __forceinline__ void pv8(f32x16* o, const char* Vt, const v8i32 p8, int r32, int hi) {
;   const int sw = (r32 >> 2) & 3, a0 = r32 * 64 + (((hi * 2) ^ sw) << 4), a1 = r32 * 64 + (((hi * 2 + 1) ^ sw) << 4);
; #pragma unroll
;   for (int d0 = 0; d0 < 4; ++d0) {
;     const v8i32 vf = cat8(*reinterpret_cast<const v4i32*>(Vt + d0 * 2048 + a0), *reinterpret_cast<const v4i32*>(Vt + d0 * 2048 + a1));
;     o[d0] = __builtin_amdgcn_mfma_scale_f32_32x32x64_f8f6f4(p8, vf, o[d0], 0, 0, 0, 127, 0, 127); }
; }
; __device__ __forceinline__ void qkt9(f32x16& p0, f32x16& p1, const char* Kn, const char* Kr, const v8i32* qf, const float init, int r32, int hi) {
; #pragma unroll
;   for (int r = 0; r < 16; ++r) { p0[r] = init; p1[r] = init; }
; #pragma unroll
;   for (int s = 0; s < 2; ++s) { const int c0 = s * 4 + hi * 2;
;     const v8i32 a0 = cat8(*reinterpret_cast<const v4i32*>(Kn + KN8SW(r32, c0)), *reinterpret_cast<const v4i32*>(Kn + KN8SW(r32, c0 + 1)));
;     const v8i32 a1 = cat8(*reinterpret_cast<const v4i32*>(Kn + 4096 + KN8SW(r32, c0)), *reinterpret_cast<const v4i32*>(Kn + 4096 + KN8SW(r32, c0 + 1)));
;     p0 = __builtin_amdgcn_mfma_scale_f32_32x32x64_f8f6f4(a0, qf[s], p0, 0, 0, 0, 127, 0, 124);
;     p1 = __builtin_amdgcn_mfma_scale_f32_32x32x64_f8f6f4(a1, qf[s], p1, 0, 0, 0, 127, 0, 124); }
;   { const int c0 = hi * 2;
.Lmla_h5_cont:
	s_add_i32 s30, s30, 1
	s_cmpk_lt_u32 s30, 42
	s_cbranch_scc1 .LBB0_1321
	ds_read_b128 v[114:117], v215 offset:24576
	ds_read_b128 v[118:121], v216 offset:24576
	ds_read_b128 v[222:225], v215 offset:28672
	ds_read_b128 v[226:229], v216 offset:28672
	s_add_i32 m0, s98, 0xa800
	s_nop 0
	global_load_lds_dwordx4 v176, s[18:19]
	s_add_i32 m0, s98, 0xc800
	s_nop 0
	global_load_lds_dwordx4 v178, s[16:17]
	s_add_i32 m0, s98, 0xe800
	s_nop 0
	global_load_lds_dwordx4 v[180:181], off
	v_exp_f32_e32 v0, v82
	v_exp_f32_e32 v177, v83
	v_exp_f32_e32 v179, v84
	v_exp_f32_e32 v254, v85
	v_add_f32_e32 v219, v0, v177
	v_cvt_pk_fp8_f32 v246, v0, v177
	v_add_f32_e32 v219, v179, v219
	v_add_f32_e32 v219, v254, v219
	v_cvt_pk_fp8_f32 v246, v179, v254 op_sel:[0,0,1]
	s_waitcnt lgkmcnt(2)
	v_mfma_scale_f32_32x32x64_f8f6f4 v[114:129], v[114:121], v[146:153], v[230:245], v194, v193 op_sel_hi:[0,0,0]
	v_exp_f32_e32 v0, v86
	v_exp_f32_e32 v177, v87
	v_exp_f32_e32 v179, v88
	v_exp_f32_e32 v254, v89
	v_add_f32_e32 v219, v0, v219
	v_add_f32_e32 v219, v177, v219
	v_cvt_pk_fp8_f32 v247, v0, v177
	v_add_f32_e32 v219, v179, v219
	v_add_f32_e32 v219, v254, v219
	v_cvt_pk_fp8_f32 v247, v179, v254 op_sel:[0,0,1]
	ds_read_b128 v[82:85], v213 offset:24576
	ds_read_b128 v[86:89], v214 offset:24576
	s_waitcnt lgkmcnt(2)
	v_mfma_scale_f32_32x32x64_f8f6f4 v[98:113], v[222:229], v[146:153], v[230:245], v194, v193 op_sel_hi:[0,0,0]
	ds_read_b128 v[222:225], v213 offset:28672
	ds_read_b128 v[226:229], v214 offset:28672
	v_exp_f32_e32 v0, v90
	v_exp_f32_e32 v177, v91
	v_exp_f32_e32 v179, v92
	v_exp_f32_e32 v254, v93
	v_add_f32_e32 v219, v0, v219
	v_add_f32_e32 v219, v177, v219
	v_cvt_pk_fp8_f32 v248, v0, v177
	v_add_f32_e32 v219, v179, v219
	v_add_f32_e32 v219, v254, v219
	v_cvt_pk_fp8_f32 v248, v179, v254 op_sel:[0,0,1]
	v_exp_f32_e32 v0, v94
	v_exp_f32_e32 v177, v95
	v_exp_f32_e32 v179, v96
	v_exp_f32_e32 v254, v97
	v_add_f32_e32 v219, v0, v219
	v_add_f32_e32 v219, v177, v219
	v_cvt_pk_fp8_f32 v249, v0, v177
	v_add_f32_e32 v219, v179, v219
	v_add_f32_e32 v219, v254, v219
	v_cvt_pk_fp8_f32 v249, v179, v254 op_sel:[0,0,1]
	ds_read_b128 v[90:93], v185 offset:36864
	ds_read_b128 v[94:97], v186 offset:36864
	s_waitcnt lgkmcnt(4)
	v_mfma_scale_f32_32x32x64_f8f6f4 v[114:129], v[82:89], v[138:145], v[114:129], v194, v193 op_sel_hi:[0,0,0]
	v_exp_f32_e32 v0, v66
	v_exp_f32_e32 v177, v67
	v_exp_f32_e32 v179, v68
	v_exp_f32_e32 v254, v69
	v_add_f32_e32 v219, v0, v219
	v_add_f32_e32 v219, v177, v219
	v_cvt_pk_fp8_f32 v250, v0, v177
	v_add_f32_e32 v219, v179, v219
	v_add_f32_e32 v219, v254, v219
	v_cvt_pk_fp8_f32 v250, v179, v254 op_sel:[0,0,1]
	s_waitcnt lgkmcnt(2)
	v_mfma_scale_f32_32x32x64_f8f6f4 v[98:113], v[222:229], v[138:145], v[98:113], v194, v193 op_sel_hi:[0,0,0]
	ds_read_b128 v[222:225], v185 offset:38912
	ds_read_b128 v[226:229], v186 offset:38912
	v_exp_f32_e32 v0, v70
	v_exp_f32_e32 v177, v71
	v_exp_f32_e32 v179, v72
	v_exp_f32_e32 v254, v73
	v_add_f32_e32 v219, v0, v219
	v_add_f32_e32 v219, v177, v219
	v_cvt_pk_fp8_f32 v251, v0, v177
	v_add_f32_e32 v219, v179, v219
	v_add_f32_e32 v219, v254, v219
	v_cvt_pk_fp8_f32 v251, v179, v254 op_sel:[0,0,1]
	v_exp_f32_e32 v0, v74
	v_exp_f32_e32 v177, v75
	v_exp_f32_e32 v179, v76
	v_exp_f32_e32 v254, v77
	v_add_f32_e32 v219, v0, v219
	v_add_f32_e32 v219, v177, v219
	v_cvt_pk_fp8_f32 v252, v0, v177
	v_add_f32_e32 v219, v179, v219
	v_add_f32_e32 v219, v254, v219
	v_cvt_pk_fp8_f32 v252, v179, v254 op_sel:[0,0,1]
	s_waitcnt lgkmcnt(2)
	v_mfma_scale_f32_32x32x64_f8f6f4 v[114:129], v[90:97], v[130:137], v[114:129], v194, v193 op_sel_hi:[0,0,0]
	v_exp_f32_e32 v0, v78
	v_exp_f32_e32 v177, v79
	v_exp_f32_e32 v179, v80
	v_exp_f32_e32 v254, v81
	v_add_f32_e32 v219, v0, v219
	v_add_f32_e32 v219, v177, v219
	v_cvt_pk_fp8_f32 v253, v0, v177
	v_add_f32_e32 v219, v179, v219
	v_add_f32_e32 v219, v254, v219
	v_cvt_pk_fp8_f32 v253, v179, v254 op_sel:[0,0,1]
	ds_read_b128 v[90:93], v185 offset:0
	ds_read_b128 v[94:97], v186 offset:0
	ds_read_b128 v[82:85], v185 offset:2048
	ds_read_b128 v[86:89], v186 offset:2048
	ds_read_b128 v[74:77], v185 offset:4096
	ds_read_b128 v[78:81], v186 offset:4096
	ds_read_b128 v[66:69], v185 offset:6144
	ds_read_b128 v[70:73], v186 offset:6144
	s_waitcnt lgkmcnt(8)
	v_mfma_scale_f32_32x32x64_f8f6f4 v[98:113], v[222:229], v[130:137], v[98:113], v194, v193 op_sel_hi:[0,0,0]
	v_mov_b32_e32 v0, v219
	s_nop 1
	v_permlane32_swap_b32_e32 v219, v0
	v_add_f32_e32 v219, v219, v0
	v_fma_f32 v209, v209, v218, v219
	v_add_u32_e32 v176, 0x2000, v176
	v_add_u32_e32 v178, 0x20000, v178
	s_mov_b64 s[20:21], 0x1000
	v_lshl_add_u64 v[180:181], v[180:181], 0, s[20:21]
	v_max_f32_e32 v177, v114, v115
	v_max3_f32 v177, v177, v116, v117
	v_max3_f32 v177, v177, v118, v119
	v_max3_f32 v177, v177, v120, v121
	v_max3_f32 v177, v177, v122, v123
	v_max3_f32 v177, v177, v124, v125
	v_max3_f32 v177, v177, v126, v127
	v_max3_f32 v177, v177, v128, v129
	s_waitcnt lgkmcnt(6)
	v_mfma_scale_f32_32x32x64_f8f6f4 v[50:65], v[246:253], v[90:97], v[50:65], v194, v194 op_sel_hi:[0,0,0]
	v_max_f32_e32 v0, v98, v99
	v_max3_f32 v0, v0, v100, v101
	v_max3_f32 v0, v0, v102, v103
	s_waitcnt lgkmcnt(4)
	v_mfma_scale_f32_32x32x64_f8f6f4 v[34:49], v[246:253], v[82:89], v[34:49], v194, v194 op_sel_hi:[0,0,0]
	v_max3_f32 v0, v0, v104, v105
	v_max3_f32 v0, v0, v106, v107
	v_max3_f32 v0, v0, v108, v109
	s_waitcnt lgkmcnt(2)
	v_mfma_scale_f32_32x32x64_f8f6f4 v[18:33], v[246:253], v[74:81], v[18:33], v194, v194 op_sel_hi:[0,0,0]
	v_max3_f32 v0, v0, v110, v111
	v_max3_f32 v0, v0, v112, v113
	v_max_f32_e32 v177, v177, v0
	v_mov_b32_e32 v0, v177
	v_mov_b32_e32 v221, 1.0
	s_waitcnt lgkmcnt(0)
	v_mfma_scale_f32_32x32x64_f8f6f4 v[2:17], v[246:253], v[66:73], v[2:17], v194, v194 op_sel_hi:[0,0,0]
	s_waitcnt vmcnt(0)
	s_waitcnt lgkmcnt(0)
	s_barrier
	v_permlane32_swap_b32_e32 v177, v0
	v_max_f32_e32 v177, v177, v0
	v_cmp_nge_f32_e32 vcc, s90, v177
	s_cbranch_vccnz .Lmla_p0_newmax

; __device__ __forceinline__ void finishSM9(f32x16& p0, f32x16& p1, float alpha, float& l_reg, v8i32& p8) {
; #pragma unroll
;   for (int r = 0; r < 16; ++r) { p0[r] = __builtin_amdgcn_exp2f(p0[r]); p1[r] = __builtin_amdgcn_exp2f(p1[r]); }
;   float ps = 0;
; #pragma unroll
;   for (int r = 0; r < 16; ++r) ps += p0[r];
; #pragma unroll
;   for (int r = 0; r < 16; ++r) ps += p1[r];
;   { auto rr = __builtin_amdgcn_permlane32_swap(__float_as_uint(ps), __float_as_uint(ps), false, false);
;     ps = __uint_as_float(rr[0]) + __uint_as_float(rr[1]); }
;   l_reg = l_reg * alpha + ps;
; #pragma unroll
;   for (int g = 0; g < 4; ++g) {
;     int w = __builtin_amdgcn_cvt_pk_fp8_f32(p0[4 * g], p0[4 * g + 1], 0, false); p8[g] = __builtin_amdgcn_cvt_pk_fp8_f32(p0[4 * g + 2], p0[4 * g + 3], w, true);
;     int u = __builtin_amdgcn_cvt_pk_fp8_f32(p1[4 * g], p1[4 * g + 1], 0, false); p8[4 + g] = __builtin_amdgcn_cvt_pk_fp8_f32(p1[4 * g + 2], p1[4 * g + 3], u, true); }
; }
; __device__ __forceinline__ void pv8(f32x16* o, const char* Vt, const v8i32 p8, int r32, int hi) {
;   const int sw = (r32 >> 2) & 3, a0 = r32 * 64 + (((hi * 2) ^ sw) << 4), a1 = r32 * 64 + (((hi * 2 + 1) ^ sw) << 4);
; #pragma unroll
;   for (int d0 = 0; d0 < 4; ++d0) {
;     const v8i32 vf = cat8(*reinterpret_cast<const v4i32*>(Vt + d0 * 2048 + a0), *reinterpret_cast<const v4i32*>(Vt + d0 * 2048 + a1));
;     o[d0] = __builtin_amdgcn_mfma_scale_f32_32x32x64_f8f6f4(p8, vf, o[d0], 0, 0, 0, 127, 0, 127); }
; }
; __device__ __forceinline__ void qkt9(f32x16& p0, f32x16& p1, const char* Kn, const char* Kr, const v8i32* qf, const float init, int r32, int hi) {
; #pragma unroll
;   for (int r = 0; r < 16; ++r) { p0[r] = init; p1[r] = init; }
; #pragma unroll
;   for (int s = 0; s < 2; ++s) { const int c0 = s * 4 + hi * 2;
;     const v8i32 a0 = cat8(*reinterpret_cast<const v4i32*>(Kn + KN8SW(r32, c0)), *reinterpret_cast<const v4i32*>(Kn + KN8SW(r32, c0 + 1)));
;     const v8i32 a1 = cat8(*reinterpret_cast<const v4i32*>(Kn + 4096 + KN8SW(r32, c0)), *reinterpret_cast<const v4i32*>(Kn + 4096 + KN8SW(r32, c0 + 1)));
;     p0 = __builtin_amdgcn_mfma_scale_f32_32x32x64_f8f6f4(a0, qf[s], p0, 0, 0, 0, 127, 0, 124);
;     p1 = __builtin_amdgcn_mfma_scale_f32_32x32x64_f8f6f4(a1, qf[s], p1, 0, 0, 0, 127, 0, 124); }
;   { const int c0 = hi * 2;
.Lmla_stag_loop:
	ds_read_b128 v[114:117], v215 offset:24576
	ds_read_b128 v[118:121], v216 offset:24576
	ds_read_b128 v[222:225], v215 offset:28672
	ds_read_b128 v[226:229], v216 offset:28672
	v_exp_f32_e32 v0, v82
	v_exp_f32_e32 v177, v83
	v_exp_f32_e32 v179, v84
	v_exp_f32_e32 v254, v85
	v_add_f32_e32 v219, v0, v177
	v_cvt_pk_fp8_f32 v246, v0, v177
	v_add_f32_e32 v219, v179, v219
	v_add_f32_e32 v219, v254, v219
	v_cvt_pk_fp8_f32 v246, v179, v254 op_sel:[0,0,1]
	s_waitcnt lgkmcnt(2)
	v_mfma_scale_f32_32x32x64_f8f6f4 v[114:129], v[114:121], v[146:153], v[230:245], v194, v193 op_sel_hi:[0,0,0]
	v_exp_f32_e32 v0, v86
	v_exp_f32_e32 v177, v87
	v_exp_f32_e32 v179, v88
	v_exp_f32_e32 v254, v89
	v_add_f32_e32 v219, v0, v219
	v_add_f32_e32 v219, v177, v219
	v_cvt_pk_fp8_f32 v247, v0, v177
	v_add_f32_e32 v219, v179, v219
	v_add_f32_e32 v219, v254, v219
	v_cvt_pk_fp8_f32 v247, v179, v254 op_sel:[0,0,1]
	ds_read_b128 v[82:85], v213 offset:24576
	ds_read_b128 v[86:89], v214 offset:24576
	s_waitcnt lgkmcnt(2)
	v_mfma_scale_f32_32x32x64_f8f6f4 v[98:113], v[222:229], v[146:153], v[230:245], v194, v193 op_sel_hi:[0,0,0]
	ds_read_b128 v[222:225], v213 offset:28672
	ds_read_b128 v[226:229], v214 offset:28672
	v_exp_f32_e32 v0, v90
	v_exp_f32_e32 v177, v91
	v_exp_f32_e32 v179, v92
	v_exp_f32_e32 v254, v93
	v_add_f32_e32 v219, v0, v219
	v_add_f32_e32 v219, v177, v219
	v_cvt_pk_fp8_f32 v248, v0, v177
	v_add_f32_e32 v219, v179, v219
	v_add_f32_e32 v219, v254, v219
	v_cvt_pk_fp8_f32 v248, v179, v254 op_sel:[0,0,1]
	v_exp_f32_e32 v0, v94
	v_exp_f32_e32 v177, v95
	v_exp_f32_e32 v179, v96
	v_exp_f32_e32 v254, v97
	v_add_f32_e32 v219, v0, v219
	v_add_f32_e32 v219, v177, v219
	v_cvt_pk_fp8_f32 v249, v0, v177
	v_add_f32_e32 v219, v179, v219
	v_add_f32_e32 v219, v254, v219
	v_cvt_pk_fp8_f32 v249, v179, v254 op_sel:[0,0,1]
	ds_read_b128 v[90:93], v185 offset:36864
	ds_read_b128 v[94:97], v186 offset:36864
	s_waitcnt lgkmcnt(4)
	v_mfma_scale_f32_32x32x64_f8f6f4 v[114:129], v[82:89], v[138:145], v[114:129], v194, v193 op_sel_hi:[0,0,0]
	v_exp_f32_e32 v0, v66
	v_exp_f32_e32 v177, v67
	v_exp_f32_e32 v179, v68
	v_exp_f32_e32 v254, v69
	v_add_f32_e32 v219, v0, v219
	v_add_f32_e32 v219, v177, v219
	v_cvt_pk_fp8_f32 v250, v0, v177
	v_add_f32_e32 v219, v179, v219
	v_add_f32_e32 v219, v254, v219
	v_cvt_pk_fp8_f32 v250, v179, v254 op_sel:[0,0,1]
	s_waitcnt lgkmcnt(2)
	v_mfma_scale_f32_32x32x64_f8f6f4 v[98:113], v[222:229], v[138:145], v[98:113], v194, v193 op_sel_hi:[0,0,0]
	ds_read_b128 v[222:225], v185 offset:38912
	ds_read_b128 v[226:229], v186 offset:38912
	v_exp_f32_e32 v0, v70
	v_exp_f32_e32 v177, v71
	v_exp_f32_e32 v179, v72
	v_exp_f32_e32 v254, v73
	v_add_f32_e32 v219, v0, v219
	v_add_f32_e32 v219, v177, v219
	v_cvt_pk_fp8_f32 v251, v0, v177
	v_add_f32_e32 v219, v179, v219
	v_add_f32_e32 v219, v254, v219
	v_cvt_pk_fp8_f32 v251, v179, v254 op_sel:[0,0,1]
	v_exp_f32_e32 v0, v74
	v_exp_f32_e32 v177, v75
	v_exp_f32_e32 v179, v76
	v_exp_f32_e32 v254, v77
	v_add_f32_e32 v219, v0, v219
	v_add_f32_e32 v219, v177, v219
	v_cvt_pk_fp8_f32 v252, v0, v177
	v_add_f32_e32 v219, v179, v219
	v_add_f32_e32 v219, v254, v219
	v_cvt_pk_fp8_f32 v252, v179, v254 op_sel:[0,0,1]
	s_waitcnt lgkmcnt(2)
	v_mfma_scale_f32_32x32x64_f8f6f4 v[114:129], v[90:97], v[130:137], v[114:129], v194, v193 op_sel_hi:[0,0,0]
	v_exp_f32_e32 v0, v78
	v_exp_f32_e32 v177, v79
	v_exp_f32_e32 v179, v80
	v_exp_f32_e32 v254, v81
	v_add_f32_e32 v219, v0, v219
	v_add_f32_e32 v219, v177, v219
	v_cvt_pk_fp8_f32 v253, v0, v177
	v_add_f32_e32 v219, v179, v219
	v_add_f32_e32 v219, v254, v219
	v_cvt_pk_fp8_f32 v253, v179, v254 op_sel:[0,0,1]
	ds_read_b128 v[90:93], v185 offset:0
	ds_read_b128 v[94:97], v186 offset:0
	ds_read_b128 v[82:85], v185 offset:2048
	ds_read_b128 v[86:89], v186 offset:2048
	ds_read_b128 v[74:77], v185 offset:4096
	ds_read_b128 v[78:81], v186 offset:4096
	ds_read_b128 v[66:69], v185 offset:6144
	ds_read_b128 v[70:73], v186 offset:6144
	s_waitcnt lgkmcnt(8)
	v_mfma_scale_f32_32x32x64_f8f6f4 v[98:113], v[222:229], v[130:137], v[98:113], v194, v193 op_sel_hi:[0,0,0]
	v_mov_b32_e32 v0, v219
	s_nop 1
	v_permlane32_swap_b32_e32 v219, v0
	v_add_f32_e32 v219, v219, v0
	v_fma_f32 v209, v209, v218, v219
	v_max_f32_e32 v177, v114, v115
	v_max3_f32 v177, v177, v116, v117
	v_max3_f32 v177, v177, v118, v119
	v_max3_f32 v177, v177, v120, v121
	v_max3_f32 v177, v177, v122, v123
	v_max3_f32 v177, v177, v124, v125
	v_max3_f32 v177, v177, v126, v127
	v_max3_f32 v177, v177, v128, v129
	s_waitcnt lgkmcnt(6)
	v_mfma_scale_f32_32x32x64_f8f6f4 v[50:65], v[246:253], v[90:97], v[50:65], v194, v194 op_sel_hi:[0,0,0]
	s_waitcnt lgkmcnt(4)
	v_mfma_scale_f32_32x32x64_f8f6f4 v[34:49], v[246:253], v[82:89], v[34:49], v194, v194 op_sel_hi:[0,0,0]
	s_waitcnt vmcnt(0)
	s_waitcnt lgkmcnt(0)
	s_barrier
	v_max_f32_e32 v0, v98, v99
	v_max3_f32 v0, v0, v100, v101
	v_max3_f32 v0, v0, v102, v103
	v_max3_f32 v0, v0, v104, v105
	s_waitcnt lgkmcnt(2)
	v_mfma_scale_f32_32x32x64_f8f6f4 v[18:33], v[246:253], v[74:81], v[18:33], v194, v194 op_sel_hi:[0,0,0]
	s_add_i32 m0, s98, 0x0
	s_nop 0
	global_load_lds_dwordx4 v176, s[18:19]
	s_add_i32 m0, s98, 0x4000
	s_nop 0
	global_load_lds_dwordx4 v178, s[16:17]
	v_add_u32_e32 v176, 0x2000, v176
	v_add_u32_e32 v178, 0x20000, v178
	v_max3_f32 v0, v0, v106, v107
	v_max3_f32 v0, v0, v108, v109
	v_max3_f32 v0, v0, v110, v111
	v_max3_f32 v0, v0, v112, v113
	s_waitcnt lgkmcnt(0)
	v_mfma_scale_f32_32x32x64_f8f6f4 v[2:17], v[246:253], v[66:73], v[2:17], v194, v194 op_sel_hi:[0,0,0]
	v_max_f32_e32 v177, v177, v0
	v_mov_b32_e32 v0, v177
	v_mov_b32_e32 v221, 1.0
	s_nop 0
	v_permlane32_swap_b32_e32 v177, v0
	v_max_f32_e32 v177, v177, v0
	v_cmp_nge_f32_e32 vcc, s90, v177
	s_cbranch_vccnz .Lmla_s0_newmax
; __device__ __forceinline__ void finishSM9(f32x16& p0, f32x16& p1, float alpha, float& l_reg, v8i32& p8) {
; #pragma unroll
;   for (int r = 0; r < 16; ++r) { p0[r] = __builtin_amdgcn_exp2f(p0[r]); p1[r] = __builtin_amdgcn_exp2f(p1[r]); }
;   float ps = 0;
; #pragma unroll
;   for (int r = 0; r < 16; ++r) ps += p0[r];
; #pragma unroll
;   for (int r = 0; r < 16; ++r) ps += p1[r];
;   { auto rr = __builtin_amdgcn_permlane32_swap(__float_as_uint(ps), __float_as_uint(ps), false, false);
;     ps = __uint_as_float(rr[0]) + __uint_as_float(rr[1]); }
;   l_reg = l_reg * alpha + ps;
; #pragma unroll
;   for (int g = 0; g < 4; ++g) {
;     int w = __builtin_amdgcn_cvt_pk_fp8_f32(p0[4 * g], p0[4 * g + 1], 0, false); p8[g] = __builtin_amdgcn_cvt_pk_fp8_f32(p0[4 * g + 2], p0[4 * g + 3], w, true);
;     int u = __builtin_amdgcn_cvt_pk_fp8_f32(p1[4 * g], p1[4 * g + 1], 0, false); p8[4 + g] = __builtin_amdgcn_cvt_pk_fp8_f32(p1[4 * g + 2], p1[4 * g + 3], u, true); }
; }
; __device__ __forceinline__ void pv8(f32x16* o, const char* Vt, const v8i32 p8, int r32, int hi) {
;   const int sw = (r32 >> 2) & 3, a0 = r32 * 64 + (((hi * 2) ^ sw) << 4), a1 = r32 * 64 + (((hi * 2 + 1) ^ sw) << 4);
; #pragma unroll
;   for (int d0 = 0; d0 < 4; ++d0) {
;     const v8i32 vf = cat8(*reinterpret_cast<const v4i32*>(Vt + d0 * 2048 + a0), *reinterpret_cast<const v4i32*>(Vt + d0 * 2048 + a1));
;     o[d0] = __builtin_amdgcn_mfma_scale_f32_32x32x64_f8f6f4(p8, vf, o[d0], 0, 0, 0, 127, 0, 127); }
; }
; __device__ __forceinline__ void qkt9(f32x16& p0, f32x16& p1, const char* Kn, const char* Kr, const v8i32* qf, const float init, int r32, int hi) {
; #pragma unroll
;   for (int r = 0; r < 16; ++r) { p0[r] = init; p1[r] = init; }
; #pragma unroll
;   for (int s = 0; s < 2; ++s) { const int c0 = s * 4 + hi * 2;
;     const v8i32 a0 = cat8(*reinterpret_cast<const v4i32*>(Kn + KN8SW(r32, c0)), *reinterpret_cast<const v4i32*>(Kn + KN8SW(r32, c0 + 1)));
;     const v8i32 a1 = cat8(*reinterpret_cast<const v4i32*>(Kn + 4096 + KN8SW(r32, c0)), *reinterpret_cast<const v4i32*>(Kn + 4096 + KN8SW(r32, c0 + 1)));
;     p0 = __builtin_amdgcn_mfma_scale_f32_32x32x64_f8f6f4(a0, qf[s], p0, 0, 0, 0, 127, 0, 124);
;     p1 = __builtin_amdgcn_mfma_scale_f32_32x32x64_f8f6f4(a1, qf[s], p1, 0, 0, 0, 127, 0, 124); }
;   { const int c0 = hi * 2;
.Lmla_s0_cont:
	ds_read_b128 v[82:85], v215 offset:51200
	ds_read_b128 v[86:89], v216 offset:51200
	ds_read_b128 v[222:225], v215 offset:55296
	ds_read_b128 v[226:229], v216 offset:55296
	v_exp_f32_e32 v0, v114
	v_exp_f32_e32 v177, v115
	v_exp_f32_e32 v179, v116
	v_exp_f32_e32 v254, v117
	v_add_f32_e32 v219, v0, v177
	v_cvt_pk_fp8_f32 v246, v0, v177
	v_add_f32_e32 v219, v179, v219
	v_add_f32_e32 v219, v254, v219
	v_cvt_pk_fp8_f32 v246, v179, v254 op_sel:[0,0,1]
	s_waitcnt lgkmcnt(2)
	v_mfma_scale_f32_32x32x64_f8f6f4 v[82:97], v[82:89], v[146:153], v[230:245], v194, v193 op_sel_hi:[0,0,0]
	v_exp_f32_e32 v0, v118
	v_exp_f32_e32 v177, v119
	v_exp_f32_e32 v179, v120
	v_exp_f32_e32 v254, v121
	v_add_f32_e32 v219, v0, v219
	v_add_f32_e32 v219, v177, v219
	v_cvt_pk_fp8_f32 v247, v0, v177
	v_add_f32_e32 v219, v179, v219
	v_add_f32_e32 v219, v254, v219
	v_cvt_pk_fp8_f32 v247, v179, v254 op_sel:[0,0,1]
	ds_read_b128 v[114:117], v213 offset:51200
	ds_read_b128 v[118:121], v214 offset:51200
	s_waitcnt lgkmcnt(2)
	v_mfma_scale_f32_32x32x64_f8f6f4 v[66:81], v[222:229], v[146:153], v[230:245], v194, v193 op_sel_hi:[0,0,0]
	ds_read_b128 v[222:225], v213 offset:55296
	ds_read_b128 v[226:229], v214 offset:55296
	v_exp_f32_e32 v0, v122
	v_exp_f32_e32 v177, v123
	v_exp_f32_e32 v179, v124
	v_exp_f32_e32 v254, v125
	v_add_f32_e32 v219, v0, v219
	v_add_f32_e32 v219, v177, v219
	v_cvt_pk_fp8_f32 v248, v0, v177
	v_add_f32_e32 v219, v179, v219
	v_add_f32_e32 v219, v254, v219
	v_cvt_pk_fp8_f32 v248, v179, v254 op_sel:[0,0,1]
	v_exp_f32_e32 v0, v126
	v_exp_f32_e32 v177, v127
	v_exp_f32_e32 v179, v128
	v_exp_f32_e32 v254, v129
	v_add_f32_e32 v219, v0, v219
	v_add_f32_e32 v219, v177, v219
	v_cvt_pk_fp8_f32 v249, v0, v177
	v_add_f32_e32 v219, v179, v219
	v_add_f32_e32 v219, v254, v219
	v_cvt_pk_fp8_f32 v249, v179, v254 op_sel:[0,0,1]
	ds_read_b128 v[122:125], v185 offset:59392
	ds_read_b128 v[126:129], v186 offset:59392
	s_waitcnt lgkmcnt(4)
	v_mfma_scale_f32_32x32x64_f8f6f4 v[82:97], v[114:121], v[138:145], v[82:97], v194, v193 op_sel_hi:[0,0,0]
	v_exp_f32_e32 v0, v98
	v_exp_f32_e32 v177, v99
	v_exp_f32_e32 v179, v100
	v_exp_f32_e32 v254, v101
	v_add_f32_e32 v219, v0, v219
	v_add_f32_e32 v219, v177, v219
	v_cvt_pk_fp8_f32 v250, v0, v177
	v_add_f32_e32 v219, v179, v219
	v_add_f32_e32 v219, v254, v219
	v_cvt_pk_fp8_f32 v250, v179, v254 op_sel:[0,0,1]
	s_waitcnt lgkmcnt(2)
	v_mfma_scale_f32_32x32x64_f8f6f4 v[66:81], v[222:229], v[138:145], v[66:81], v194, v193 op_sel_hi:[0,0,0]
	ds_read_b128 v[222:225], v185 offset:61440
	ds_read_b128 v[226:229], v186 offset:61440
	v_exp_f32_e32 v0, v102
	v_exp_f32_e32 v177, v103
	v_exp_f32_e32 v179, v104
	v_exp_f32_e32 v254, v105
	v_add_f32_e32 v219, v0, v219
	v_add_f32_e32 v219, v177, v219
	v_cvt_pk_fp8_f32 v251, v0, v177
	v_add_f32_e32 v219, v179, v219
	v_add_f32_e32 v219, v254, v219
	v_cvt_pk_fp8_f32 v251, v179, v254 op_sel:[0,0,1]
	v_exp_f32_e32 v0, v106
	v_exp_f32_e32 v177, v107
	v_exp_f32_e32 v179, v108
	v_exp_f32_e32 v254, v109
	v_add_f32_e32 v219, v0, v219
	v_add_f32_e32 v219, v177, v219
	v_cvt_pk_fp8_f32 v252, v0, v177
	v_add_f32_e32 v219, v179, v219
	v_add_f32_e32 v219, v254, v219
	v_cvt_pk_fp8_f32 v252, v179, v254 op_sel:[0,0,1]
	s_waitcnt lgkmcnt(2)
	v_mfma_scale_f32_32x32x64_f8f6f4 v[82:97], v[122:129], v[130:137], v[82:97], v194, v193 op_sel_hi:[0,0,0]
	v_exp_f32_e32 v0, v110
	v_exp_f32_e32 v177, v111
	v_exp_f32_e32 v179, v112
	v_exp_f32_e32 v254, v113
	v_add_f32_e32 v219, v0, v219
	v_add_f32_e32 v219, v177, v219
	v_cvt_pk_fp8_f32 v253, v0, v177
	v_add_f32_e32 v219, v179, v219
	v_add_f32_e32 v219, v254, v219
	v_cvt_pk_fp8_f32 v253, v179, v254 op_sel:[0,0,1]
	ds_read_b128 v[122:125], v185 offset:8192
	ds_read_b128 v[126:129], v186 offset:8192
	ds_read_b128 v[114:117], v185 offset:10240
	ds_read_b128 v[118:121], v186 offset:10240
	ds_read_b128 v[106:109], v185 offset:12288
	ds_read_b128 v[110:113], v186 offset:12288
	ds_read_b128 v[98:101], v185 offset:14336
	ds_read_b128 v[102:105], v186 offset:14336
	s_waitcnt lgkmcnt(8)
	v_mfma_scale_f32_32x32x64_f8f6f4 v[66:81], v[222:229], v[130:137], v[66:81], v194, v193 op_sel_hi:[0,0,0]
	v_mov_b32_e32 v0, v219
	s_nop 1
	v_permlane32_swap_b32_e32 v219, v0
	v_add_f32_e32 v219, v219, v0
	v_fma_f32 v209, v209, v221, v219
	v_max_f32_e32 v177, v82, v83
	v_max3_f32 v177, v177, v84, v85
	v_max3_f32 v177, v177, v86, v87
	v_max3_f32 v177, v177, v88, v89
	v_max3_f32 v177, v177, v90, v91
	v_max3_f32 v177, v177, v92, v93
	v_max3_f32 v177, v177, v94, v95
	v_max3_f32 v177, v177, v96, v97
	s_waitcnt lgkmcnt(6)
	v_mfma_scale_f32_32x32x64_f8f6f4 v[50:65], v[246:253], v[122:129], v[50:65], v194, v194 op_sel_hi:[0,0,0]
	s_waitcnt lgkmcnt(4)
	v_mfma_scale_f32_32x32x64_f8f6f4 v[34:49], v[246:253], v[114:121], v[34:49], v194, v194 op_sel_hi:[0,0,0]
	s_waitcnt vmcnt(0)
	s_waitcnt lgkmcnt(0)
	s_barrier
	v_max_f32_e32 v0, v66, v67
	v_max3_f32 v0, v0, v68, v69
	v_max3_f32 v0, v0, v70, v71
	v_max3_f32 v0, v0, v72, v73
	s_waitcnt lgkmcnt(2)
	v_mfma_scale_f32_32x32x64_f8f6f4 v[18:33], v[246:253], v[106:113], v[18:33], v194, v194 op_sel_hi:[0,0,0]
	s_add_i32 m0, s98, 0x2000
	s_nop 0
	global_load_lds_dwordx4 v176, s[18:19]
	s_add_i32 m0, s98, 0x6000
	s_nop 0
	global_load_lds_dwordx4 v178, s[16:17]
	v_add_u32_e32 v176, 0x2000, v176
	v_add_u32_e32 v178, 0x20000, v178
	v_max3_f32 v0, v0, v74, v75
	v_max3_f32 v0, v0, v76, v77
	v_max3_f32 v0, v0, v78, v79
	v_max3_f32 v0, v0, v80, v81
	s_waitcnt lgkmcnt(0)
	v_mfma_scale_f32_32x32x64_f8f6f4 v[2:17], v[246:253], v[98:105], v[2:17], v194, v194 op_sel_hi:[0,0,0]
	v_max_f32_e32 v177, v177, v0
	v_mov_b32_e32 v0, v177
	v_mov_b32_e32 v218, 1.0
	s_nop 0
	v_permlane32_swap_b32_e32 v177, v0
	v_max_f32_e32 v177, v177, v0
	v_cmp_nge_f32_e32 vcc, s90, v177
	s_cbranch_vccnz .Lmla_s1_newmax
; __device__ __forceinline__ void finishSM9(f32x16& p0, f32x16& p1, float alpha, float& l_reg, v8i32& p8) {
; #pragma unroll
;   for (int r = 0; r < 16; ++r) { p0[r] = __builtin_amdgcn_exp2f(p0[r]); p1[r] = __builtin_amdgcn_exp2f(p1[r]); }
;   float ps = 0;
; #pragma unroll
;   for (int r = 0; r < 16; ++r) ps += p0[r];
; #pragma unroll
;   for (int r = 0; r < 16; ++r) ps += p1[r];
;   { auto rr = __builtin_amdgcn_permlane32_swap(__float_as_uint(ps), __float_as_uint(ps), false, false);
;     ps = __uint_as_float(rr[0]) + __uint_as_float(rr[1]); }
;   l_reg = l_reg * alpha + ps;
; #pragma unroll
;   for (int g = 0; g < 4; ++g) {
;     int w = __builtin_amdgcn_cvt_pk_fp8_f32(p0[4 * g], p0[4 * g + 1], 0, false); p8[g] = __builtin_amdgcn_cvt_pk_fp8_f32(p0[4 * g + 2], p0[4 * g + 3], w, true);
;     int u = __builtin_amdgcn_cvt_pk_fp8_f32(p1[4 * g], p1[4 * g + 1], 0, false); p8[4 + g] = __builtin_amdgcn_cvt_pk_fp8_f32(p1[4 * g + 2], p1[4 * g + 3], u, true); }
; }
; __device__ __forceinline__ void pv8(f32x16* o, const char* Vt, const v8i32 p8, int r32, int hi) {
;   const int sw = (r32 >> 2) & 3, a0 = r32 * 64 + (((hi * 2) ^ sw) << 4), a1 = r32 * 64 + (((hi * 2 + 1) ^ sw) << 4);
; #pragma unroll
;   for (int d0 = 0; d0 < 4; ++d0) {
;     const v8i32 vf = cat8(*reinterpret_cast<const v4i32*>(Vt + d0 * 2048 + a0), *reinterpret_cast<const v4i32*>(Vt + d0 * 2048 + a1));
;     o[d0] = __builtin_amdgcn_mfma_scale_f32_32x32x64_f8f6f4(p8, vf, o[d0], 0, 0, 0, 127, 0, 127); }
; }
; __device__ __forceinline__ void qkt9(f32x16& p0, f32x16& p1, const char* Kn, const char* Kr, const v8i32* qf, const float init, int r32, int hi) {
; #pragma unroll
;   for (int r = 0; r < 16; ++r) { p0[r] = init; p1[r] = init; }
; #pragma unroll
;   for (int s = 0; s < 2; ++s) { const int c0 = s * 4 + hi * 2;
;     const v8i32 a0 = cat8(*reinterpret_cast<const v4i32*>(Kn + KN8SW(r32, c0)), *reinterpret_cast<const v4i32*>(Kn + KN8SW(r32, c0 + 1)));
;     const v8i32 a1 = cat8(*reinterpret_cast<const v4i32*>(Kn + 4096 + KN8SW(r32, c0)), *reinterpret_cast<const v4i32*>(Kn + 4096 + KN8SW(r32, c0 + 1)));
;     p0 = __builtin_amdgcn_mfma_scale_f32_32x32x64_f8f6f4(a0, qf[s], p0, 0, 0, 0, 127, 0, 124);
;     p1 = __builtin_amdgcn_mfma_scale_f32_32x32x64_f8f6f4(a1, qf[s], p1, 0, 0, 0, 127, 0, 124); }
;   { const int c0 = hi * 2;
.Lmla_s1_cont:
	ds_read_b128 v[114:117], v215 offset:16384
	ds_read_b128 v[118:121], v216 offset:16384
	ds_read_b128 v[222:225], v215 offset:20480
	ds_read_b128 v[226:229], v216 offset:20480
	v_exp_f32_e32 v0, v82
	v_exp_f32_e32 v177, v83
	v_exp_f32_e32 v179, v84
	v_exp_f32_e32 v254, v85
	v_add_f32_e32 v219, v0, v177
	v_cvt_pk_fp8_f32 v246, v0, v177
	v_add_f32_e32 v219, v179, v219
	v_add_f32_e32 v219, v254, v219
	v_cvt_pk_fp8_f32 v246, v179, v254 op_sel:[0,0,1]
	s_waitcnt lgkmcnt(2)
	v_mfma_scale_f32_32x32x64_f8f6f4 v[114:129], v[114:121], v[146:153], v[230:245], v194, v193 op_sel_hi:[0,0,0]
	v_exp_f32_e32 v0, v86
	v_exp_f32_e32 v177, v87
	v_exp_f32_e32 v179, v88
	v_exp_f32_e32 v254, v89
	v_add_f32_e32 v219, v0, v219
	v_add_f32_e32 v219, v177, v219
	v_cvt_pk_fp8_f32 v247, v0, v177
	v_add_f32_e32 v219, v179, v219
	v_add_f32_e32 v219, v254, v219
	v_cvt_pk_fp8_f32 v247, v179, v254 op_sel:[0,0,1]
	ds_read_b128 v[82:85], v213 offset:16384
	ds_read_b128 v[86:89], v214 offset:16384
	s_waitcnt lgkmcnt(2)
	v_mfma_scale_f32_32x32x64_f8f6f4 v[98:113], v[222:229], v[146:153], v[230:245], v194, v193 op_sel_hi:[0,0,0]
	ds_read_b128 v[222:225], v213 offset:20480
	ds_read_b128 v[226:229], v214 offset:20480
	v_exp_f32_e32 v0, v90
	v_exp_f32_e32 v177, v91
	v_exp_f32_e32 v179, v92
	v_exp_f32_e32 v254, v93
	v_add_f32_e32 v219, v0, v219
	v_add_f32_e32 v219, v177, v219
	v_cvt_pk_fp8_f32 v248, v0, v177
	v_add_f32_e32 v219, v179, v219
	v_add_f32_e32 v219, v254, v219
	v_cvt_pk_fp8_f32 v248, v179, v254 op_sel:[0,0,1]
	v_exp_f32_e32 v0, v94
	v_exp_f32_e32 v177, v95
	v_exp_f32_e32 v179, v96
	v_exp_f32_e32 v254, v97
	v_add_f32_e32 v219, v0, v219
	v_add_f32_e32 v219, v177, v219
	v_cvt_pk_fp8_f32 v249, v0, v177
	v_add_f32_e32 v219, v179, v219
	v_add_f32_e32 v219, v254, v219
	v_cvt_pk_fp8_f32 v249, v179, v254 op_sel:[0,0,1]
	ds_read_b128 v[90:93], v185 offset:32768
	ds_read_b128 v[94:97], v186 offset:32768
	s_waitcnt lgkmcnt(4)
	v_mfma_scale_f32_32x32x64_f8f6f4 v[114:129], v[82:89], v[138:145], v[114:129], v194, v193 op_sel_hi:[0,0,0]
	v_exp_f32_e32 v0, v66
	v_exp_f32_e32 v177, v67
	v_exp_f32_e32 v179, v68
	v_exp_f32_e32 v254, v69
	v_add_f32_e32 v219, v0, v219
	v_add_f32_e32 v219, v177, v219
	v_cvt_pk_fp8_f32 v250, v0, v177
	v_add_f32_e32 v219, v179, v219
	v_add_f32_e32 v219, v254, v219
	v_cvt_pk_fp8_f32 v250, v179, v254 op_sel:[0,0,1]
	s_waitcnt lgkmcnt(2)
	v_mfma_scale_f32_32x32x64_f8f6f4 v[98:113], v[222:229], v[138:145], v[98:113], v194, v193 op_sel_hi:[0,0,0]
	ds_read_b128 v[222:225], v185 offset:34816
	ds_read_b128 v[226:229], v186 offset:34816
	v_exp_f32_e32 v0, v70
	v_exp_f32_e32 v177, v71
	v_exp_f32_e32 v179, v72
	v_exp_f32_e32 v254, v73
	v_add_f32_e32 v219, v0, v219
	v_add_f32_e32 v219, v177, v219
	v_cvt_pk_fp8_f32 v251, v0, v177
	v_add_f32_e32 v219, v179, v219
	v_add_f32_e32 v219, v254, v219
	v_cvt_pk_fp8_f32 v251, v179, v254 op_sel:[0,0,1]
	v_exp_f32_e32 v0, v74
	v_exp_f32_e32 v177, v75
	v_exp_f32_e32 v179, v76
	v_exp_f32_e32 v254, v77
	v_add_f32_e32 v219, v0, v219
	v_add_f32_e32 v219, v177, v219
	v_cvt_pk_fp8_f32 v252, v0, v177
	v_add_f32_e32 v219, v179, v219
	v_add_f32_e32 v219, v254, v219
	v_cvt_pk_fp8_f32 v252, v179, v254 op_sel:[0,0,1]
	s_waitcnt lgkmcnt(2)
	v_mfma_scale_f32_32x32x64_f8f6f4 v[114:129], v[90:97], v[130:137], v[114:129], v194, v193 op_sel_hi:[0,0,0]
	v_exp_f32_e32 v0, v78
	v_exp_f32_e32 v177, v79
	v_exp_f32_e32 v179, v80
	v_exp_f32_e32 v254, v81
	v_add_f32_e32 v219, v0, v219
	v_add_f32_e32 v219, v177, v219
	v_cvt_pk_fp8_f32 v253, v0, v177
	v_add_f32_e32 v219, v179, v219
	v_add_f32_e32 v219, v254, v219
	v_cvt_pk_fp8_f32 v253, v179, v254 op_sel:[0,0,1]
	ds_read_b128 v[90:93], v185 offset:43008
	ds_read_b128 v[94:97], v186 offset:43008
	ds_read_b128 v[82:85], v185 offset:45056
	ds_read_b128 v[86:89], v186 offset:45056
	ds_read_b128 v[74:77], v185 offset:47104
	ds_read_b128 v[78:81], v186 offset:47104
	ds_read_b128 v[66:69], v185 offset:49152
	ds_read_b128 v[70:73], v186 offset:49152
	s_waitcnt lgkmcnt(8)
	v_mfma_scale_f32_32x32x64_f8f6f4 v[98:113], v[222:229], v[130:137], v[98:113], v194, v193 op_sel_hi:[0,0,0]
	v_mov_b32_e32 v0, v219
	s_nop 1
	v_permlane32_swap_b32_e32 v219, v0
	v_add_f32_e32 v219, v219, v0
	v_fma_f32 v209, v209, v218, v219
	v_max_f32_e32 v177, v114, v115
	v_max3_f32 v177, v177, v116, v117
	v_max3_f32 v177, v177, v118, v119
	v_max3_f32 v177, v177, v120, v121
	v_max3_f32 v177, v177, v122, v123
	v_max3_f32 v177, v177, v124, v125
	v_max3_f32 v177, v177, v126, v127
	v_max3_f32 v177, v177, v128, v129
	s_waitcnt lgkmcnt(6)
	v_mfma_scale_f32_32x32x64_f8f6f4 v[50:65], v[246:253], v[90:97], v[50:65], v194, v194 op_sel_hi:[0,0,0]
	s_waitcnt lgkmcnt(4)
	v_mfma_scale_f32_32x32x64_f8f6f4 v[34:49], v[246:253], v[82:89], v[34:49], v194, v194 op_sel_hi:[0,0,0]
	s_waitcnt vmcnt(0)
	s_waitcnt lgkmcnt(0)
	s_barrier
	v_max_f32_e32 v0, v98, v99
	v_max3_f32 v0, v0, v100, v101
	v_max3_f32 v0, v0, v102, v103
	v_max3_f32 v0, v0, v104, v105
	s_waitcnt lgkmcnt(2)
	v_mfma_scale_f32_32x32x64_f8f6f4 v[18:33], v[246:253], v[74:81], v[18:33], v194, v194 op_sel_hi:[0,0,0]
	s_add_i32 m0, s98, 0xa800
	s_nop 0
	global_load_lds_dwordx4 v176, s[18:19]
	s_add_i32 m0, s98, 0xc800
	s_nop 0
	global_load_lds_dwordx4 v178, s[16:17]
	v_add_u32_e32 v176, 0x2000, v176
	v_add_u32_e32 v178, 0x20000, v178
	v_max3_f32 v0, v0, v106, v107
	v_max3_f32 v0, v0, v108, v109
	v_max3_f32 v0, v0, v110, v111
	v_max3_f32 v0, v0, v112, v113
	s_waitcnt lgkmcnt(0)
	v_mfma_scale_f32_32x32x64_f8f6f4 v[2:17], v[246:253], v[66:73], v[2:17], v194, v194 op_sel_hi:[0,0,0]
	v_max_f32_e32 v177, v177, v0
	v_mov_b32_e32 v0, v177
	v_mov_b32_e32 v221, 1.0
	s_nop 0
	v_permlane32_swap_b32_e32 v177, v0
	v_max_f32_e32 v177, v177, v0
	v_cmp_nge_f32_e32 vcc, s90, v177
	s_cbranch_vccnz .Lmla_s2_newmax
; __device__ __forceinline__ void finishSM9(f32x16& p0, f32x16& p1, float alpha, float& l_reg, v8i32& p8) {
; #pragma unroll
;   for (int r = 0; r < 16; ++r) { p0[r] = __builtin_amdgcn_exp2f(p0[r]); p1[r] = __builtin_amdgcn_exp2f(p1[r]); }
;   float ps = 0;
; #pragma unroll
;   for (int r = 0; r < 16; ++r) ps += p0[r];
; #pragma unroll
;   for (int r = 0; r < 16; ++r) ps += p1[r];
;   { auto rr = __builtin_amdgcn_permlane32_swap(__float_as_uint(ps), __float_as_uint(ps), false, false);
;     ps = __uint_as_float(rr[0]) + __uint_as_float(rr[1]); }
;   l_reg = l_reg * alpha + ps;
; #pragma unroll
;   for (int g = 0; g < 4; ++g) {
;     int w = __builtin_amdgcn_cvt_pk_fp8_f32(p0[4 * g], p0[4 * g + 1], 0, false); p8[g] = __builtin_amdgcn_cvt_pk_fp8_f32(p0[4 * g + 2], p0[4 * g + 3], w, true);
;     int u = __builtin_amdgcn_cvt_pk_fp8_f32(p1[4 * g], p1[4 * g + 1], 0, false); p8[4 + g] = __builtin_amdgcn_cvt_pk_fp8_f32(p1[4 * g + 2], p1[4 * g + 3], u, true); }
; }
; __device__ __forceinline__ void pv8(f32x16* o, const char* Vt, const v8i32 p8, int r32, int hi) {
;   const int sw = (r32 >> 2) & 3, a0 = r32 * 64 + (((hi * 2) ^ sw) << 4), a1 = r32 * 64 + (((hi * 2 + 1) ^ sw) << 4);
; #pragma unroll
;   for (int d0 = 0; d0 < 4; ++d0) {
;     const v8i32 vf = cat8(*reinterpret_cast<const v4i32*>(Vt + d0 * 2048 + a0), *reinterpret_cast<const v4i32*>(Vt + d0 * 2048 + a1));
;     o[d0] = __builtin_amdgcn_mfma_scale_f32_32x32x64_f8f6f4(p8, vf, o[d0], 0, 0, 0, 127, 0, 127); }
; }
; __device__ __forceinline__ void qkt9(f32x16& p0, f32x16& p1, const char* Kn, const char* Kr, const v8i32* qf, const float init, int r32, int hi) {
; #pragma unroll
;   for (int r = 0; r < 16; ++r) { p0[r] = init; p1[r] = init; }
; #pragma unroll
;   for (int s = 0; s < 2; ++s) { const int c0 = s * 4 + hi * 2;
;     const v8i32 a0 = cat8(*reinterpret_cast<const v4i32*>(Kn + KN8SW(r32, c0)), *reinterpret_cast<const v4i32*>(Kn + KN8SW(r32, c0 + 1)));
;     const v8i32 a1 = cat8(*reinterpret_cast<const v4i32*>(Kn + 4096 + KN8SW(r32, c0)), *reinterpret_cast<const v4i32*>(Kn + 4096 + KN8SW(r32, c0 + 1)));
;     p0 = __builtin_amdgcn_mfma_scale_f32_32x32x64_f8f6f4(a0, qf[s], p0, 0, 0, 0, 127, 0, 124);
;     p1 = __builtin_amdgcn_mfma_scale_f32_32x32x64_f8f6f4(a1, qf[s], p1, 0, 0, 0, 127, 0, 124); }
;   { const int c0 = hi * 2;
.Lmla_s2_cont:
	ds_read_b128 v[82:85], v215 offset:24576
	ds_read_b128 v[86:89], v216 offset:24576
	ds_read_b128 v[222:225], v215 offset:28672
	ds_read_b128 v[226:229], v216 offset:28672
	v_exp_f32_e32 v0, v114
	v_exp_f32_e32 v177, v115
	v_exp_f32_e32 v179, v116
	v_exp_f32_e32 v254, v117
	v_add_f32_e32 v219, v0, v177
	v_cvt_pk_fp8_f32 v246, v0, v177
	v_add_f32_e32 v219, v179, v219
	v_add_f32_e32 v219, v254, v219
	v_cvt_pk_fp8_f32 v246, v179, v254 op_sel:[0,0,1]
	s_waitcnt lgkmcnt(2)
	v_mfma_scale_f32_32x32x64_f8f6f4 v[82:97], v[82:89], v[146:153], v[230:245], v194, v193 op_sel_hi:[0,0,0]
	v_exp_f32_e32 v0, v118
	v_exp_f32_e32 v177, v119
	v_exp_f32_e32 v179, v120
	v_exp_f32_e32 v254, v121
	v_add_f32_e32 v219, v0, v219
	v_add_f32_e32 v219, v177, v219
	v_cvt_pk_fp8_f32 v247, v0, v177
	v_add_f32_e32 v219, v179, v219
	v_add_f32_e32 v219, v254, v219
	v_cvt_pk_fp8_f32 v247, v179, v254 op_sel:[0,0,1]
	ds_read_b128 v[114:117], v213 offset:24576
	ds_read_b128 v[118:121], v214 offset:24576
	s_waitcnt lgkmcnt(2)
	v_mfma_scale_f32_32x32x64_f8f6f4 v[66:81], v[222:229], v[146:153], v[230:245], v194, v193 op_sel_hi:[0,0,0]
	ds_read_b128 v[222:225], v213 offset:28672
	ds_read_b128 v[226:229], v214 offset:28672
	v_exp_f32_e32 v0, v122
	v_exp_f32_e32 v177, v123
	v_exp_f32_e32 v179, v124
	v_exp_f32_e32 v254, v125
	v_add_f32_e32 v219, v0, v219
	v_add_f32_e32 v219, v177, v219
	v_cvt_pk_fp8_f32 v248, v0, v177
	v_add_f32_e32 v219, v179, v219
	v_add_f32_e32 v219, v254, v219
	v_cvt_pk_fp8_f32 v248, v179, v254 op_sel:[0,0,1]
	v_exp_f32_e32 v0, v126
	v_exp_f32_e32 v177, v127
	v_exp_f32_e32 v179, v128
	v_exp_f32_e32 v254, v129
	v_add_f32_e32 v219, v0, v219
	v_add_f32_e32 v219, v177, v219
	v_cvt_pk_fp8_f32 v249, v0, v177
	v_add_f32_e32 v219, v179, v219
	v_add_f32_e32 v219, v254, v219
	v_cvt_pk_fp8_f32 v249, v179, v254 op_sel:[0,0,1]
	ds_read_b128 v[122:125], v185 offset:36864
	ds_read_b128 v[126:129], v186 offset:36864
	s_waitcnt lgkmcnt(4)
	v_mfma_scale_f32_32x32x64_f8f6f4 v[82:97], v[114:121], v[138:145], v[82:97], v194, v193 op_sel_hi:[0,0,0]
	v_exp_f32_e32 v0, v98
	v_exp_f32_e32 v177, v99
	v_exp_f32_e32 v179, v100
	v_exp_f32_e32 v254, v101
	v_add_f32_e32 v219, v0, v219
	v_add_f32_e32 v219, v177, v219
	v_cvt_pk_fp8_f32 v250, v0, v177
	v_add_f32_e32 v219, v179, v219
	v_add_f32_e32 v219, v254, v219
	v_cvt_pk_fp8_f32 v250, v179, v254 op_sel:[0,0,1]
	s_waitcnt lgkmcnt(2)
	v_mfma_scale_f32_32x32x64_f8f6f4 v[66:81], v[222:229], v[138:145], v[66:81], v194, v193 op_sel_hi:[0,0,0]
	ds_read_b128 v[222:225], v185 offset:38912
	ds_read_b128 v[226:229], v186 offset:38912
	v_exp_f32_e32 v0, v102
	v_exp_f32_e32 v177, v103
	v_exp_f32_e32 v179, v104
	v_exp_f32_e32 v254, v105
	v_add_f32_e32 v219, v0, v219
	v_add_f32_e32 v219, v177, v219
	v_cvt_pk_fp8_f32 v251, v0, v177
	v_add_f32_e32 v219, v179, v219
	v_add_f32_e32 v219, v254, v219
	v_cvt_pk_fp8_f32 v251, v179, v254 op_sel:[0,0,1]
	v_exp_f32_e32 v0, v106
	v_exp_f32_e32 v177, v107
	v_exp_f32_e32 v179, v108
	v_exp_f32_e32 v254, v109
	v_add_f32_e32 v219, v0, v219
	v_add_f32_e32 v219, v177, v219
	v_cvt_pk_fp8_f32 v252, v0, v177
	v_add_f32_e32 v219, v179, v219
	v_add_f32_e32 v219, v254, v219
	v_cvt_pk_fp8_f32 v252, v179, v254 op_sel:[0,0,1]
	s_waitcnt lgkmcnt(2)
	v_mfma_scale_f32_32x32x64_f8f6f4 v[82:97], v[122:129], v[130:137], v[82:97], v194, v193 op_sel_hi:[0,0,0]
	v_exp_f32_e32 v0, v110
	v_exp_f32_e32 v177, v111
	v_exp_f32_e32 v179, v112
	v_exp_f32_e32 v254, v113
	v_add_f32_e32 v219, v0, v219
	v_add_f32_e32 v219, v177, v219
	v_cvt_pk_fp8_f32 v253, v0, v177
	v_add_f32_e32 v219, v179, v219
	v_add_f32_e32 v219, v254, v219
	v_cvt_pk_fp8_f32 v253, v179, v254 op_sel:[0,0,1]
	ds_read_b128 v[122:125], v185 offset:0
	ds_read_b128 v[126:129], v186 offset:0
	ds_read_b128 v[114:117], v185 offset:2048
	ds_read_b128 v[118:121], v186 offset:2048
	ds_read_b128 v[106:109], v185 offset:4096
	ds_read_b128 v[110:113], v186 offset:4096
	ds_read_b128 v[98:101], v185 offset:6144
	ds_read_b128 v[102:105], v186 offset:6144
	s_waitcnt lgkmcnt(8)
	v_mfma_scale_f32_32x32x64_f8f6f4 v[66:81], v[222:229], v[130:137], v[66:81], v194, v193 op_sel_hi:[0,0,0]
	v_mov_b32_e32 v0, v219
	s_nop 1
	v_permlane32_swap_b32_e32 v219, v0
	v_add_f32_e32 v219, v219, v0
	v_fma_f32 v209, v209, v221, v219
	v_max_f32_e32 v177, v82, v83
	v_max3_f32 v177, v177, v84, v85
	v_max3_f32 v177, v177, v86, v87
	v_max3_f32 v177, v177, v88, v89
	v_max3_f32 v177, v177, v90, v91
	v_max3_f32 v177, v177, v92, v93
	v_max3_f32 v177, v177, v94, v95
	v_max3_f32 v177, v177, v96, v97
	s_waitcnt lgkmcnt(6)
	v_mfma_scale_f32_32x32x64_f8f6f4 v[50:65], v[246:253], v[122:129], v[50:65], v194, v194 op_sel_hi:[0,0,0]
	s_waitcnt lgkmcnt(4)
	v_mfma_scale_f32_32x32x64_f8f6f4 v[34:49], v[246:253], v[114:121], v[34:49], v194, v194 op_sel_hi:[0,0,0]
	s_waitcnt vmcnt(0)
	s_waitcnt lgkmcnt(0)
	s_barrier
	v_max_f32_e32 v0, v66, v67
	v_max3_f32 v0, v0, v68, v69
	v_max3_f32 v0, v0, v70, v71
	v_max3_f32 v0, v0, v72, v73
	s_waitcnt lgkmcnt(2)
	v_mfma_scale_f32_32x32x64_f8f6f4 v[18:33], v[246:253], v[106:113], v[18:33], v194, v194 op_sel_hi:[0,0,0]
	s_add_i32 m0, s98, 0x0
	s_nop 0
	global_load_lds_dwordx4 v176, s[18:19]
	s_add_i32 m0, s98, 0x4000
	s_nop 0
	global_load_lds_dwordx4 v178, s[16:17]
	v_add_u32_e32 v176, 0x2000, v176
	v_add_u32_e32 v178, 0x20000, v178
	v_max3_f32 v0, v0, v74, v75
	v_max3_f32 v0, v0, v76, v77
	v_max3_f32 v0, v0, v78, v79
	v_max3_f32 v0, v0, v80, v81
	s_waitcnt lgkmcnt(0)
	v_mfma_scale_f32_32x32x64_f8f6f4 v[2:17], v[246:253], v[98:105], v[2:17], v194, v194 op_sel_hi:[0,0,0]
	v_max_f32_e32 v177, v177, v0
	v_mov_b32_e32 v0, v177
	v_mov_b32_e32 v218, 1.0
	s_nop 0
	v_permlane32_swap_b32_e32 v177, v0
	v_max_f32_e32 v177, v177, v0
	v_cmp_nge_f32_e32 vcc, s90, v177
	s_cbranch_vccnz .Lmla_s3_newmax
; __device__ __forceinline__ void finishSM9(f32x16& p0, f32x16& p1, float alpha, float& l_reg, v8i32& p8) {
; #pragma unroll
;   for (int r = 0; r < 16; ++r) { p0[r] = __builtin_amdgcn_exp2f(p0[r]); p1[r] = __builtin_amdgcn_exp2f(p1[r]); }
;   float ps = 0;
; #pragma unroll
;   for (int r = 0; r < 16; ++r) ps += p0[r];
; #pragma unroll
;   for (int r = 0; r < 16; ++r) ps += p1[r];
;   { auto rr = __builtin_amdgcn_permlane32_swap(__float_as_uint(ps), __float_as_uint(ps), false, false);
;     ps = __uint_as_float(rr[0]) + __uint_as_float(rr[1]); }
;   l_reg = l_reg * alpha + ps;
; #pragma unroll
;   for (int g = 0; g < 4; ++g) {
;     int w = __builtin_amdgcn_cvt_pk_fp8_f32(p0[4 * g], p0[4 * g + 1], 0, false); p8[g] = __builtin_amdgcn_cvt_pk_fp8_f32(p0[4 * g + 2], p0[4 * g + 3], w, true);
;     int u = __builtin_amdgcn_cvt_pk_fp8_f32(p1[4 * g], p1[4 * g + 1], 0, false); p8[4 + g] = __builtin_amdgcn_cvt_pk_fp8_f32(p1[4 * g + 2], p1[4 * g + 3], u, true); }
; }
; __device__ __forceinline__ void pv8(f32x16* o, const char* Vt, const v8i32 p8, int r32, int hi) {
;   const int sw = (r32 >> 2) & 3, a0 = r32 * 64 + (((hi * 2) ^ sw) << 4), a1 = r32 * 64 + (((hi * 2 + 1) ^ sw) << 4);
; #pragma unroll
;   for (int d0 = 0; d0 < 4; ++d0) {
;     const v8i32 vf = cat8(*reinterpret_cast<const v4i32*>(Vt + d0 * 2048 + a0), *reinterpret_cast<const v4i32*>(Vt + d0 * 2048 + a1));
;     o[d0] = __builtin_amdgcn_mfma_scale_f32_32x32x64_f8f6f4(p8, vf, o[d0], 0, 0, 0, 127, 0, 127); }
; }
; __device__ __forceinline__ void qkt9(f32x16& p0, f32x16& p1, const char* Kn, const char* Kr, const v8i32* qf, const float init, int r32, int hi) {
; #pragma unroll
;   for (int r = 0; r < 16; ++r) { p0[r] = init; p1[r] = init; }
; #pragma unroll
;   for (int s = 0; s < 2; ++s) { const int c0 = s * 4 + hi * 2;
;     const v8i32 a0 = cat8(*reinterpret_cast<const v4i32*>(Kn + KN8SW(r32, c0)), *reinterpret_cast<const v4i32*>(Kn + KN8SW(r32, c0 + 1)));
;     const v8i32 a1 = cat8(*reinterpret_cast<const v4i32*>(Kn + 4096 + KN8SW(r32, c0)), *reinterpret_cast<const v4i32*>(Kn + 4096 + KN8SW(r32, c0 + 1)));
;     p0 = __builtin_amdgcn_mfma_scale_f32_32x32x64_f8f6f4(a0, qf[s], p0, 0, 0, 0, 127, 0, 124);
;     p1 = __builtin_amdgcn_mfma_scale_f32_32x32x64_f8f6f4(a1, qf[s], p1, 0, 0, 0, 127, 0, 124); }
;   { const int c0 = hi * 2;
.Lmla_s3_cont:
	ds_read_b128 v[114:117], v215 offset:51200
	ds_read_b128 v[118:121], v216 offset:51200
	ds_read_b128 v[222:225], v215 offset:55296
	ds_read_b128 v[226:229], v216 offset:55296
	v_exp_f32_e32 v0, v82
	v_exp_f32_e32 v177, v83
	v_exp_f32_e32 v179, v84
	v_exp_f32_e32 v254, v85
	v_add_f32_e32 v219, v0, v177
	v_cvt_pk_fp8_f32 v246, v0, v177
	v_add_f32_e32 v219, v179, v219
	v_add_f32_e32 v219, v254, v219
	v_cvt_pk_fp8_f32 v246, v179, v254 op_sel:[0,0,1]
	s_waitcnt lgkmcnt(2)
	v_mfma_scale_f32_32x32x64_f8f6f4 v[114:129], v[114:121], v[146:153], v[230:245], v194, v193 op_sel_hi:[0,0,0]
	v_exp_f32_e32 v0, v86
	v_exp_f32_e32 v177, v87
	v_exp_f32_e32 v179, v88
	v_exp_f32_e32 v254, v89
	v_add_f32_e32 v219, v0, v219
	v_add_f32_e32 v219, v177, v219
	v_cvt_pk_fp8_f32 v247, v0, v177
	v_add_f32_e32 v219, v179, v219
	v_add_f32_e32 v219, v254, v219
	v_cvt_pk_fp8_f32 v247, v179, v254 op_sel:[0,0,1]
	ds_read_b128 v[82:85], v213 offset:51200
	ds_read_b128 v[86:89], v214 offset:51200
	s_waitcnt lgkmcnt(2)
	v_mfma_scale_f32_32x32x64_f8f6f4 v[98:113], v[222:229], v[146:153], v[230:245], v194, v193 op_sel_hi:[0,0,0]
	ds_read_b128 v[222:225], v213 offset:55296
	ds_read_b128 v[226:229], v214 offset:55296
	v_exp_f32_e32 v0, v90
	v_exp_f32_e32 v177, v91
	v_exp_f32_e32 v179, v92
	v_exp_f32_e32 v254, v93
	v_add_f32_e32 v219, v0, v219
	v_add_f32_e32 v219, v177, v219
	v_cvt_pk_fp8_f32 v248, v0, v177
	v_add_f32_e32 v219, v179, v219
	v_add_f32_e32 v219, v254, v219
	v_cvt_pk_fp8_f32 v248, v179, v254 op_sel:[0,0,1]
	v_exp_f32_e32 v0, v94
	v_exp_f32_e32 v177, v95
	v_exp_f32_e32 v179, v96
	v_exp_f32_e32 v254, v97
	v_add_f32_e32 v219, v0, v219
	v_add_f32_e32 v219, v177, v219
	v_cvt_pk_fp8_f32 v249, v0, v177
	v_add_f32_e32 v219, v179, v219
	v_add_f32_e32 v219, v254, v219
	v_cvt_pk_fp8_f32 v249, v179, v254 op_sel:[0,0,1]
	ds_read_b128 v[90:93], v185 offset:59392
	ds_read_b128 v[94:97], v186 offset:59392
	s_waitcnt lgkmcnt(4)
	v_mfma_scale_f32_32x32x64_f8f6f4 v[114:129], v[82:89], v[138:145], v[114:129], v194, v193 op_sel_hi:[0,0,0]
	v_exp_f32_e32 v0, v66
	v_exp_f32_e32 v177, v67
	v_exp_f32_e32 v179, v68
	v_exp_f32_e32 v254, v69
	v_add_f32_e32 v219, v0, v219
	v_add_f32_e32 v219, v177, v219
	v_cvt_pk_fp8_f32 v250, v0, v177
	v_add_f32_e32 v219, v179, v219
	v_add_f32_e32 v219, v254, v219
	v_cvt_pk_fp8_f32 v250, v179, v254 op_sel:[0,0,1]
	s_waitcnt lgkmcnt(2)
	v_mfma_scale_f32_32x32x64_f8f6f4 v[98:113], v[222:229], v[138:145], v[98:113], v194, v193 op_sel_hi:[0,0,0]
	ds_read_b128 v[222:225], v185 offset:61440
	ds_read_b128 v[226:229], v186 offset:61440
	v_exp_f32_e32 v0, v70
	v_exp_f32_e32 v177, v71
	v_exp_f32_e32 v179, v72
	v_exp_f32_e32 v254, v73
	v_add_f32_e32 v219, v0, v219
	v_add_f32_e32 v219, v177, v219
	v_cvt_pk_fp8_f32 v251, v0, v177
	v_add_f32_e32 v219, v179, v219
	v_add_f32_e32 v219, v254, v219
	v_cvt_pk_fp8_f32 v251, v179, v254 op_sel:[0,0,1]
	v_exp_f32_e32 v0, v74
	v_exp_f32_e32 v177, v75
	v_exp_f32_e32 v179, v76
	v_exp_f32_e32 v254, v77
	v_add_f32_e32 v219, v0, v219
	v_add_f32_e32 v219, v177, v219
	v_cvt_pk_fp8_f32 v252, v0, v177
	v_add_f32_e32 v219, v179, v219
	v_add_f32_e32 v219, v254, v219
	v_cvt_pk_fp8_f32 v252, v179, v254 op_sel:[0,0,1]
	s_waitcnt lgkmcnt(2)
	v_mfma_scale_f32_32x32x64_f8f6f4 v[114:129], v[90:97], v[130:137], v[114:129], v194, v193 op_sel_hi:[0,0,0]
	v_exp_f32_e32 v0, v78
	v_exp_f32_e32 v177, v79
	v_exp_f32_e32 v179, v80
	v_exp_f32_e32 v254, v81
	v_add_f32_e32 v219, v0, v219
	v_add_f32_e32 v219, v177, v219
	v_cvt_pk_fp8_f32 v253, v0, v177
	v_add_f32_e32 v219, v179, v219
	v_add_f32_e32 v219, v254, v219
	v_cvt_pk_fp8_f32 v253, v179, v254 op_sel:[0,0,1]
	ds_read_b128 v[90:93], v185 offset:8192
	ds_read_b128 v[94:97], v186 offset:8192
	ds_read_b128 v[82:85], v185 offset:10240
	ds_read_b128 v[86:89], v186 offset:10240
	ds_read_b128 v[74:77], v185 offset:12288
	ds_read_b128 v[78:81], v186 offset:12288
	ds_read_b128 v[66:69], v185 offset:14336
	ds_read_b128 v[70:73], v186 offset:14336
	s_waitcnt lgkmcnt(8)
	v_mfma_scale_f32_32x32x64_f8f6f4 v[98:113], v[222:229], v[130:137], v[98:113], v194, v193 op_sel_hi:[0,0,0]
	v_mov_b32_e32 v0, v219
	s_nop 1
	v_permlane32_swap_b32_e32 v219, v0
	v_add_f32_e32 v219, v219, v0
	v_fma_f32 v209, v209, v218, v219
	v_max_f32_e32 v177, v114, v115
	v_max3_f32 v177, v177, v116, v117
	v_max3_f32 v177, v177, v118, v119
	v_max3_f32 v177, v177, v120, v121
	v_max3_f32 v177, v177, v122, v123
	v_max3_f32 v177, v177, v124, v125
	v_max3_f32 v177, v177, v126, v127
	v_max3_f32 v177, v177, v128, v129
	s_waitcnt lgkmcnt(6)
	v_mfma_scale_f32_32x32x64_f8f6f4 v[50:65], v[246:253], v[90:97], v[50:65], v194, v194 op_sel_hi:[0,0,0]
	s_waitcnt lgkmcnt(4)
	v_mfma_scale_f32_32x32x64_f8f6f4 v[34:49], v[246:253], v[82:89], v[34:49], v194, v194 op_sel_hi:[0,0,0]
	s_waitcnt vmcnt(0)
	s_waitcnt lgkmcnt(0)
	s_barrier
	v_max_f32_e32 v0, v98, v99
	v_max3_f32 v0, v0, v100, v101
	v_max3_f32 v0, v0, v102, v103
	v_max3_f32 v0, v0, v104, v105
	s_waitcnt lgkmcnt(2)
	v_mfma_scale_f32_32x32x64_f8f6f4 v[18:33], v[246:253], v[74:81], v[18:33], v194, v194 op_sel_hi:[0,0,0]
	s_add_i32 m0, s98, 0x2000
	s_nop 0
	global_load_lds_dwordx4 v176, s[18:19]
	s_add_i32 m0, s98, 0x6000
	s_nop 0
	global_load_lds_dwordx4 v178, s[16:17]
	v_add_u32_e32 v176, 0x2000, v176
	v_add_u32_e32 v178, 0x20000, v178
	v_max3_f32 v0, v0, v106, v107
	v_max3_f32 v0, v0, v108, v109
	v_max3_f32 v0, v0, v110, v111
	v_max3_f32 v0, v0, v112, v113
	s_waitcnt lgkmcnt(0)
	v_mfma_scale_f32_32x32x64_f8f6f4 v[2:17], v[246:253], v[66:73], v[2:17], v194, v194 op_sel_hi:[0,0,0]
	v_max_f32_e32 v177, v177, v0
	v_mov_b32_e32 v0, v177
	v_mov_b32_e32 v221, 1.0
	s_nop 0
	v_permlane32_swap_b32_e32 v177, v0
	v_max_f32_e32 v177, v177, v0
	v_cmp_nge_f32_e32 vcc, s90, v177
	s_cbranch_vccnz .Lmla_s4_newmax
; __device__ __forceinline__ void finishSM9(f32x16& p0, f32x16& p1, float alpha, float& l_reg, v8i32& p8) {
; #pragma unroll
;   for (int r = 0; r < 16; ++r) { p0[r] = __builtin_amdgcn_exp2f(p0[r]); p1[r] = __builtin_amdgcn_exp2f(p1[r]); }
;   float ps = 0;
; #pragma unroll
;   for (int r = 0; r < 16; ++r) ps += p0[r];
; #pragma unroll
;   for (int r = 0; r < 16; ++r) ps += p1[r];
;   { auto rr = __builtin_amdgcn_permlane32_swap(__float_as_uint(ps), __float_as_uint(ps), false, false);
;     ps = __uint_as_float(rr[0]) + __uint_as_float(rr[1]); }
;   l_reg = l_reg * alpha + ps;
; #pragma unroll
;   for (int g = 0; g < 4; ++g) {
;     int w = __builtin_amdgcn_cvt_pk_fp8_f32(p0[4 * g], p0[4 * g + 1], 0, false); p8[g] = __builtin_amdgcn_cvt_pk_fp8_f32(p0[4 * g + 2], p0[4 * g + 3], w, true);
;     int u = __builtin_amdgcn_cvt_pk_fp8_f32(p1[4 * g], p1[4 * g + 1], 0, false); p8[4 + g] = __builtin_amdgcn_cvt_pk_fp8_f32(p1[4 * g + 2], p1[4 * g + 3], u, true); }
; }
; __device__ __forceinline__ void pv8(f32x16* o, const char* Vt, const v8i32 p8, int r32, int hi) {
;   const int sw = (r32 >> 2) & 3, a0 = r32 * 64 + (((hi * 2) ^ sw) << 4), a1 = r32 * 64 + (((hi * 2 + 1) ^ sw) << 4);
; #pragma unroll
;   for (int d0 = 0; d0 < 4; ++d0) {
;     const v8i32 vf = cat8(*reinterpret_cast<const v4i32*>(Vt + d0 * 2048 + a0), *reinterpret_cast<const v4i32*>(Vt + d0 * 2048 + a1));
;     o[d0] = __builtin_amdgcn_mfma_scale_f32_32x32x64_f8f6f4(p8, vf, o[d0], 0, 0, 0, 127, 0, 127); }
; }
; __device__ __forceinline__ void qkt9(f32x16& p0, f32x16& p1, const char* Kn, const char* Kr, const v8i32* qf, const float init, int r32, int hi) {
; #pragma unroll
;   for (int r = 0; r < 16; ++r) { p0[r] = init; p1[r] = init; }
; #pragma unroll
;   for (int s = 0; s < 2; ++s) { const int c0 = s * 4 + hi * 2;
;     const v8i32 a0 = cat8(*reinterpret_cast<const v4i32*>(Kn + KN8SW(r32, c0)), *reinterpret_cast<const v4i32*>(Kn + KN8SW(r32, c0 + 1)));
;     const v8i32 a1 = cat8(*reinterpret_cast<const v4i32*>(Kn + 4096 + KN8SW(r32, c0)), *reinterpret_cast<const v4i32*>(Kn + 4096 + KN8SW(r32, c0 + 1)));
;     p0 = __builtin_amdgcn_mfma_scale_f32_32x32x64_f8f6f4(a0, qf[s], p0, 0, 0, 0, 127, 0, 124);
;     p1 = __builtin_amdgcn_mfma_scale_f32_32x32x64_f8f6f4(a1, qf[s], p1, 0, 0, 0, 127, 0, 124); }
;   { const int c0 = hi * 2;
.Lmla_s4_cont:
	ds_read_b128 v[82:85], v215 offset:16384
	ds_read_b128 v[86:89], v216 offset:16384
	ds_read_b128 v[222:225], v215 offset:20480
	ds_read_b128 v[226:229], v216 offset:20480
	v_exp_f32_e32 v0, v114
	v_exp_f32_e32 v177, v115
	v_exp_f32_e32 v179, v116
	v_exp_f32_e32 v254, v117
	v_add_f32_e32 v219, v0, v177
	v_cvt_pk_fp8_f32 v246, v0, v177
	v_add_f32_e32 v219, v179, v219
	v_add_f32_e32 v219, v254, v219
	v_cvt_pk_fp8_f32 v246, v179, v254 op_sel:[0,0,1]
	s_waitcnt lgkmcnt(2)
	v_mfma_scale_f32_32x32x64_f8f6f4 v[82:97], v[82:89], v[146:153], v[230:245], v194, v193 op_sel_hi:[0,0,0]
	v_exp_f32_e32 v0, v118
	v_exp_f32_e32 v177, v119
	v_exp_f32_e32 v179, v120
	v_exp_f32_e32 v254, v121
	v_add_f32_e32 v219, v0, v219
	v_add_f32_e32 v219, v177, v219
	v_cvt_pk_fp8_f32 v247, v0, v177
	v_add_f32_e32 v219, v179, v219
	v_add_f32_e32 v219, v254, v219
	v_cvt_pk_fp8_f32 v247, v179, v254 op_sel:[0,0,1]
	ds_read_b128 v[114:117], v213 offset:16384
	ds_read_b128 v[118:121], v214 offset:16384
	s_waitcnt lgkmcnt(2)
	v_mfma_scale_f32_32x32x64_f8f6f4 v[66:81], v[222:229], v[146:153], v[230:245], v194, v193 op_sel_hi:[0,0,0]
	ds_read_b128 v[222:225], v213 offset:20480
	ds_read_b128 v[226:229], v214 offset:20480
	v_exp_f32_e32 v0, v122
	v_exp_f32_e32 v177, v123
	v_exp_f32_e32 v179, v124
	v_exp_f32_e32 v254, v125
	v_add_f32_e32 v219, v0, v219
	v_add_f32_e32 v219, v177, v219
	v_cvt_pk_fp8_f32 v248, v0, v177
	v_add_f32_e32 v219, v179, v219
	v_add_f32_e32 v219, v254, v219
	v_cvt_pk_fp8_f32 v248, v179, v254 op_sel:[0,0,1]
	v_exp_f32_e32 v0, v126
	v_exp_f32_e32 v177, v127
	v_exp_f32_e32 v179, v128
	v_exp_f32_e32 v254, v129
	v_add_f32_e32 v219, v0, v219
	v_add_f32_e32 v219, v177, v219
	v_cvt_pk_fp8_f32 v249, v0, v177
	v_add_f32_e32 v219, v179, v219
	v_add_f32_e32 v219, v254, v219
	v_cvt_pk_fp8_f32 v249, v179, v254 op_sel:[0,0,1]
	ds_read_b128 v[122:125], v185 offset:32768
	ds_read_b128 v[126:129], v186 offset:32768
	s_waitcnt lgkmcnt(4)
	v_mfma_scale_f32_32x32x64_f8f6f4 v[82:97], v[114:121], v[138:145], v[82:97], v194, v193 op_sel_hi:[0,0,0]
	v_exp_f32_e32 v0, v98
	v_exp_f32_e32 v177, v99
	v_exp_f32_e32 v179, v100
	v_exp_f32_e32 v254, v101
	v_add_f32_e32 v219, v0, v219
	v_add_f32_e32 v219, v177, v219
	v_cvt_pk_fp8_f32 v250, v0, v177
	v_add_f32_e32 v219, v179, v219
	v_add_f32_e32 v219, v254, v219
	v_cvt_pk_fp8_f32 v250, v179, v254 op_sel:[0,0,1]
	s_waitcnt lgkmcnt(2)
	v_mfma_scale_f32_32x32x64_f8f6f4 v[66:81], v[222:229], v[138:145], v[66:81], v194, v193 op_sel_hi:[0,0,0]
	ds_read_b128 v[222:225], v185 offset:34816
	ds_read_b128 v[226:229], v186 offset:34816
	v_exp_f32_e32 v0, v102
	v_exp_f32_e32 v177, v103
	v_exp_f32_e32 v179, v104
	v_exp_f32_e32 v254, v105
	v_add_f32_e32 v219, v0, v219
	v_add_f32_e32 v219, v177, v219
	v_cvt_pk_fp8_f32 v251, v0, v177
	v_add_f32_e32 v219, v179, v219
	v_add_f32_e32 v219, v254, v219
	v_cvt_pk_fp8_f32 v251, v179, v254 op_sel:[0,0,1]
	v_exp_f32_e32 v0, v106
	v_exp_f32_e32 v177, v107
	v_exp_f32_e32 v179, v108
	v_exp_f32_e32 v254, v109
	v_add_f32_e32 v219, v0, v219
	v_add_f32_e32 v219, v177, v219
	v_cvt_pk_fp8_f32 v252, v0, v177
	v_add_f32_e32 v219, v179, v219
	v_add_f32_e32 v219, v254, v219
	v_cvt_pk_fp8_f32 v252, v179, v254 op_sel:[0,0,1]
	s_waitcnt lgkmcnt(2)
	v_mfma_scale_f32_32x32x64_f8f6f4 v[82:97], v[122:129], v[130:137], v[82:97], v194, v193 op_sel_hi:[0,0,0]
	v_exp_f32_e32 v0, v110
	v_exp_f32_e32 v177, v111
	v_exp_f32_e32 v179, v112
	v_exp_f32_e32 v254, v113
	v_add_f32_e32 v219, v0, v219
	v_add_f32_e32 v219, v177, v219
	v_cvt_pk_fp8_f32 v253, v0, v177
	v_add_f32_e32 v219, v179, v219
	v_add_f32_e32 v219, v254, v219
	v_cvt_pk_fp8_f32 v253, v179, v254 op_sel:[0,0,1]
	ds_read_b128 v[122:125], v185 offset:43008
	ds_read_b128 v[126:129], v186 offset:43008
	ds_read_b128 v[114:117], v185 offset:45056
	ds_read_b128 v[118:121], v186 offset:45056
	ds_read_b128 v[106:109], v185 offset:47104
	ds_read_b128 v[110:113], v186 offset:47104
	ds_read_b128 v[98:101], v185 offset:49152
	ds_read_b128 v[102:105], v186 offset:49152
	s_waitcnt lgkmcnt(8)
	v_mfma_scale_f32_32x32x64_f8f6f4 v[66:81], v[222:229], v[130:137], v[66:81], v194, v193 op_sel_hi:[0,0,0]
	v_mov_b32_e32 v0, v219
	s_nop 1
	v_permlane32_swap_b32_e32 v219, v0
	v_add_f32_e32 v219, v219, v0
	v_fma_f32 v209, v209, v221, v219
	v_max_f32_e32 v177, v82, v83
	v_max3_f32 v177, v177, v84, v85
	v_max3_f32 v177, v177, v86, v87
	v_max3_f32 v177, v177, v88, v89
	v_max3_f32 v177, v177, v90, v91
	v_max3_f32 v177, v177, v92, v93
	v_max3_f32 v177, v177, v94, v95
	v_max3_f32 v177, v177, v96, v97
	s_waitcnt lgkmcnt(6)
	v_mfma_scale_f32_32x32x64_f8f6f4 v[50:65], v[246:253], v[122:129], v[50:65], v194, v194 op_sel_hi:[0,0,0]
	s_waitcnt lgkmcnt(4)
	v_mfma_scale_f32_32x32x64_f8f6f4 v[34:49], v[246:253], v[114:121], v[34:49], v194, v194 op_sel_hi:[0,0,0]
	s_waitcnt vmcnt(0)
	s_waitcnt lgkmcnt(0)
	s_barrier
	v_max_f32_e32 v0, v66, v67
	v_max3_f32 v0, v0, v68, v69
	v_max3_f32 v0, v0, v70, v71
	v_max3_f32 v0, v0, v72, v73
	s_waitcnt lgkmcnt(2)
	v_mfma_scale_f32_32x32x64_f8f6f4 v[18:33], v[246:253], v[106:113], v[18:33], v194, v194 op_sel_hi:[0,0,0]
	s_add_i32 m0, s98, 0xa800
	s_nop 0
	global_load_lds_dwordx4 v176, s[18:19]
	s_add_i32 m0, s98, 0xc800
	s_nop 0
	global_load_lds_dwordx4 v178, s[16:17]
	v_add_u32_e32 v176, 0x2000, v176
	v_add_u32_e32 v178, 0x20000, v178
	v_max3_f32 v0, v0, v74, v75
	v_max3_f32 v0, v0, v76, v77
	v_max3_f32 v0, v0, v78, v79
	v_max3_f32 v0, v0, v80, v81
	s_waitcnt lgkmcnt(0)
	v_mfma_scale_f32_32x32x64_f8f6f4 v[2:17], v[246:253], v[98:105], v[2:17], v194, v194 op_sel_hi:[0,0,0]
	v_max_f32_e32 v177, v177, v0
	v_mov_b32_e32 v0, v177
	v_mov_b32_e32 v218, 1.0
	s_nop 0
	v_permlane32_swap_b32_e32 v177, v0
	v_max_f32_e32 v177, v177, v0
	v_cmp_nge_f32_e32 vcc, s90, v177
	s_cbranch_vccnz .Lmla_s5_newmax
; __device__ __forceinline__ void finishSM9(f32x16& p0, f32x16& p1, float alpha, float& l_reg, v8i32& p8) {
; #pragma unroll
;   for (int r = 0; r < 16; ++r) { p0[r] = __builtin_amdgcn_exp2f(p0[r]); p1[r] = __builtin_amdgcn_exp2f(p1[r]); }
;   float ps = 0;
; #pragma unroll
;   for (int r = 0; r < 16; ++r) ps += p0[r];
; #pragma unroll
;   for (int r = 0; r < 16; ++r) ps += p1[r];
;   { auto rr = __builtin_amdgcn_permlane32_swap(__float_as_uint(ps), __float_as_uint(ps), false, false);
;     ps = __uint_as_float(rr[0]) + __uint_as_float(rr[1]); }
;   l_reg = l_reg * alpha + ps;
; #pragma unroll
;   for (int g = 0; g < 4; ++g) {
;     int w = __builtin_amdgcn_cvt_pk_fp8_f32(p0[4 * g], p0[4 * g + 1], 0, false); p8[g] = __builtin_amdgcn_cvt_pk_fp8_f32(p0[4 * g + 2], p0[4 * g + 3], w, true);
;     int u = __builtin_amdgcn_cvt_pk_fp8_f32(p1[4 * g], p1[4 * g + 1], 0, false); p8[4 + g] = __builtin_amdgcn_cvt_pk_fp8_f32(p1[4 * g + 2], p1[4 * g + 3], u, true); }
; }
; __device__ __forceinline__ void pv8(f32x16* o, const char* Vt, const v8i32 p8, int r32, int hi) {
;   const int sw = (r32 >> 2) & 3, a0 = r32 * 64 + (((hi * 2) ^ sw) << 4), a1 = r32 * 64 + (((hi * 2 + 1) ^ sw) << 4);
; #pragma unroll
;   for (int d0 = 0; d0 < 4; ++d0) {
;     const v8i32 vf = cat8(*reinterpret_cast<const v4i32*>(Vt + d0 * 2048 + a0), *reinterpret_cast<const v4i32*>(Vt + d0 * 2048 + a1));
;     o[d0] = __builtin_amdgcn_mfma_scale_f32_32x32x64_f8f6f4(p8, vf, o[d0], 0, 0, 0, 127, 0, 127); }
; }
; __device__ __forceinline__ void qkt9(f32x16& p0, f32x16& p1, const char* Kn, const char* Kr, const v8i32* qf, const float init, int r32, int hi) {
; #pragma unroll
;   for (int r = 0; r < 16; ++r) { p0[r] = init; p1[r] = init; }
; #pragma unroll
;   for (int s = 0; s < 2; ++s) { const int c0 = s * 4 + hi * 2;
;     const v8i32 a0 = cat8(*reinterpret_cast<const v4i32*>(Kn + KN8SW(r32, c0)), *reinterpret_cast<const v4i32*>(Kn + KN8SW(r32, c0 + 1)));
;     const v8i32 a1 = cat8(*reinterpret_cast<const v4i32*>(Kn + 4096 + KN8SW(r32, c0)), *reinterpret_cast<const v4i32*>(Kn + 4096 + KN8SW(r32, c0 + 1)));
;     p0 = __builtin_amdgcn_mfma_scale_f32_32x32x64_f8f6f4(a0, qf[s], p0, 0, 0, 0, 127, 0, 124);
;     p1 = __builtin_amdgcn_mfma_scale_f32_32x32x64_f8f6f4(a1, qf[s], p1, 0, 0, 0, 127, 0, 124); }
;   { const int c0 = hi * 2;
.Lmla_s5_cont:
	s_add_i32 s30, s30, 1
	s_cmpk_lt_u32 s30, 42
	s_cbranch_scc1 .Lmla_stag_loop
	ds_read_b128 v[114:117], v215 offset:24576
	ds_read_b128 v[118:121], v216 offset:24576
	ds_read_b128 v[222:225], v215 offset:28672
	ds_read_b128 v[226:229], v216 offset:28672
	v_exp_f32_e32 v0, v82
	v_exp_f32_e32 v177, v83
	v_exp_f32_e32 v179, v84
	v_exp_f32_e32 v254, v85
	v_add_f32_e32 v219, v0, v177
	v_cvt_pk_fp8_f32 v246, v0, v177
	v_add_f32_e32 v219, v179, v219
	v_add_f32_e32 v219, v254, v219
	v_cvt_pk_fp8_f32 v246, v179, v254 op_sel:[0,0,1]
	s_waitcnt lgkmcnt(2)
	v_mfma_scale_f32_32x32x64_f8f6f4 v[114:129], v[114:121], v[146:153], v[230:245], v194, v193 op_sel_hi:[0,0,0]
	v_exp_f32_e32 v0, v86
	v_exp_f32_e32 v177, v87
	v_exp_f32_e32 v179, v88
	v_exp_f32_e32 v254, v89
	v_add_f32_e32 v219, v0, v219
	v_add_f32_e32 v219, v177, v219
	v_cvt_pk_fp8_f32 v247, v0, v177
	v_add_f32_e32 v219, v179, v219
	v_add_f32_e32 v219, v254, v219
	v_cvt_pk_fp8_f32 v247, v179, v254 op_sel:[0,0,1]
	ds_read_b128 v[82:85], v213 offset:24576
	ds_read_b128 v[86:89], v214 offset:24576
	s_waitcnt lgkmcnt(2)
	v_mfma_scale_f32_32x32x64_f8f6f4 v[98:113], v[222:229], v[146:153], v[230:245], v194, v193 op_sel_hi:[0,0,0]
	ds_read_b128 v[222:225], v213 offset:28672
	ds_read_b128 v[226:229], v214 offset:28672
	v_exp_f32_e32 v0, v90
	v_exp_f32_e32 v177, v91
	v_exp_f32_e32 v179, v92
	v_exp_f32_e32 v254, v93
	v_add_f32_e32 v219, v0, v219
	v_add_f32_e32 v219, v177, v219
	v_cvt_pk_fp8_f32 v248, v0, v177
	v_add_f32_e32 v219, v179, v219
	v_add_f32_e32 v219, v254, v219
	v_cvt_pk_fp8_f32 v248, v179, v254 op_sel:[0,0,1]
	v_exp_f32_e32 v0, v94
	v_exp_f32_e32 v177, v95
	v_exp_f32_e32 v179, v96
	v_exp_f32_e32 v254, v97
	v_add_f32_e32 v219, v0, v219
	v_add_f32_e32 v219, v177, v219
	v_cvt_pk_fp8_f32 v249, v0, v177
	v_add_f32_e32 v219, v179, v219
	v_add_f32_e32 v219, v254, v219
	v_cvt_pk_fp8_f32 v249, v179, v254 op_sel:[0,0,1]
	ds_read_b128 v[90:93], v185 offset:36864
	ds_read_b128 v[94:97], v186 offset:36864
	s_waitcnt lgkmcnt(4)
	v_mfma_scale_f32_32x32x64_f8f6f4 v[114:129], v[82:89], v[138:145], v[114:129], v194, v193 op_sel_hi:[0,0,0]
	v_exp_f32_e32 v0, v66
	v_exp_f32_e32 v177, v67
	v_exp_f32_e32 v179, v68
	v_exp_f32_e32 v254, v69
	v_add_f32_e32 v219, v0, v219
	v_add_f32_e32 v219, v177, v219
	v_cvt_pk_fp8_f32 v250, v0, v177
	v_add_f32_e32 v219, v179, v219
	v_add_f32_e32 v219, v254, v219
	v_cvt_pk_fp8_f32 v250, v179, v254 op_sel:[0,0,1]
	s_waitcnt lgkmcnt(2)
	v_mfma_scale_f32_32x32x64_f8f6f4 v[98:113], v[222:229], v[138:145], v[98:113], v194, v193 op_sel_hi:[0,0,0]
	ds_read_b128 v[222:225], v185 offset:38912
	ds_read_b128 v[226:229], v186 offset:38912
	v_exp_f32_e32 v0, v70
	v_exp_f32_e32 v177, v71
	v_exp_f32_e32 v179, v72
	v_exp_f32_e32 v254, v73
	v_add_f32_e32 v219, v0, v219
	v_add_f32_e32 v219, v177, v219
	v_cvt_pk_fp8_f32 v251, v0, v177
	v_add_f32_e32 v219, v179, v219
	v_add_f32_e32 v219, v254, v219
	v_cvt_pk_fp8_f32 v251, v179, v254 op_sel:[0,0,1]
	v_exp_f32_e32 v0, v74
	v_exp_f32_e32 v177, v75
	v_exp_f32_e32 v179, v76
	v_exp_f32_e32 v254, v77
	v_add_f32_e32 v219, v0, v219
	v_add_f32_e32 v219, v177, v219
	v_cvt_pk_fp8_f32 v252, v0, v177
	v_add_f32_e32 v219, v179, v219
	v_add_f32_e32 v219, v254, v219
	v_cvt_pk_fp8_f32 v252, v179, v254 op_sel:[0,0,1]
	s_waitcnt lgkmcnt(2)
	v_mfma_scale_f32_32x32x64_f8f6f4 v[114:129], v[90:97], v[130:137], v[114:129], v194, v193 op_sel_hi:[0,0,0]
	v_exp_f32_e32 v0, v78
	v_exp_f32_e32 v177, v79
	v_exp_f32_e32 v179, v80
	v_exp_f32_e32 v254, v81
	v_add_f32_e32 v219, v0, v219
	v_add_f32_e32 v219, v177, v219
	v_cvt_pk_fp8_f32 v253, v0, v177
	v_add_f32_e32 v219, v179, v219
	v_add_f32_e32 v219, v254, v219
	v_cvt_pk_fp8_f32 v253, v179, v254 op_sel:[0,0,1]
	ds_read_b128 v[90:93], v185 offset:0
	ds_read_b128 v[94:97], v186 offset:0
	ds_read_b128 v[82:85], v185 offset:2048
	ds_read_b128 v[86:89], v186 offset:2048
	ds_read_b128 v[74:77], v185 offset:4096
	ds_read_b128 v[78:81], v186 offset:4096
	ds_read_b128 v[66:69], v185 offset:6144
	ds_read_b128 v[70:73], v186 offset:6144
	s_waitcnt lgkmcnt(8)
	v_mfma_scale_f32_32x32x64_f8f6f4 v[98:113], v[222:229], v[130:137], v[98:113], v194, v193 op_sel_hi:[0,0,0]
	v_mov_b32_e32 v0, v219
	s_nop 1
	v_permlane32_swap_b32_e32 v219, v0
	v_add_f32_e32 v219, v219, v0
	v_fma_f32 v209, v209, v218, v219
	v_max_f32_e32 v177, v114, v115
	v_max3_f32 v177, v177, v116, v117
	v_max3_f32 v177, v177, v118, v119
	v_max3_f32 v177, v177, v120, v121
	v_max3_f32 v177, v177, v122, v123
	v_max3_f32 v177, v177, v124, v125
	v_max3_f32 v177, v177, v126, v127
	v_max3_f32 v177, v177, v128, v129
	s_waitcnt lgkmcnt(6)
	v_mfma_scale_f32_32x32x64_f8f6f4 v[50:65], v[246:253], v[90:97], v[50:65], v194, v194 op_sel_hi:[0,0,0]
	s_waitcnt lgkmcnt(4)
	v_mfma_scale_f32_32x32x64_f8f6f4 v[34:49], v[246:253], v[82:89], v[34:49], v194, v194 op_sel_hi:[0,0,0]
	s_waitcnt vmcnt(0)
	s_waitcnt lgkmcnt(0)
	s_barrier
	v_max_f32_e32 v0, v98, v99
	v_max3_f32 v0, v0, v100, v101
	v_max3_f32 v0, v0, v102, v103
	v_max3_f32 v0, v0, v104, v105
	s_waitcnt lgkmcnt(2)
	v_mfma_scale_f32_32x32x64_f8f6f4 v[18:33], v[246:253], v[74:81], v[18:33], v194, v194 op_sel_hi:[0,0,0]
	s_add_i32 m0, s98, 0x0
	s_nop 0
	global_load_lds_dwordx4 v176, s[18:19]
	s_add_i32 m0, s98, 0x4000
	s_nop 0
	global_load_lds_dwordx4 v178, s[16:17]
	v_add_u32_e32 v176, 0x2000, v176
	v_add_u32_e32 v178, 0x20000, v178
	v_max3_f32 v0, v0, v106, v107
	v_max3_f32 v0, v0, v108, v109
	v_max3_f32 v0, v0, v110, v111
	v_max3_f32 v0, v0, v112, v113
	s_waitcnt lgkmcnt(0)
	v_mfma_scale_f32_32x32x64_f8f6f4 v[2:17], v[246:253], v[66:73], v[2:17], v194, v194 op_sel_hi:[0,0,0]
	v_max_f32_e32 v177, v177, v0
	v_mov_b32_e32 v0, v177
	v_mov_b32_e32 v221, 1.0
	s_nop 0
	v_permlane32_swap_b32_e32 v177, v0
	v_max_f32_e32 v177, v177, v0
	v_cmp_nge_f32_e32 vcc, s90, v177
	s_cbranch_vccnz .Lmla_q0_newmax
; __device__ __forceinline__ void finishSM9(f32x16& p0, f32x16& p1, float alpha, float& l_reg, v8i32& p8) {
; #pragma unroll
;   for (int r = 0; r < 16; ++r) { p0[r] = __builtin_amdgcn_exp2f(p0[r]); p1[r] = __builtin_amdgcn_exp2f(p1[r]); }
;   float ps = 0;
; #pragma unroll
;   for (int r = 0; r < 16; ++r) ps += p0[r];
; #pragma unroll
;   for (int r = 0; r < 16; ++r) ps += p1[r];
;   { auto rr = __builtin_amdgcn_permlane32_swap(__float_as_uint(ps), __float_as_uint(ps), false, false);
;     ps = __uint_as_float(rr[0]) + __uint_as_float(rr[1]); }
;   l_reg = l_reg * alpha + ps;
; #pragma unroll
;   for (int g = 0; g < 4; ++g) {
;     int w = __builtin_amdgcn_cvt_pk_fp8_f32(p0[4 * g], p0[4 * g + 1], 0, false); p8[g] = __builtin_amdgcn_cvt_pk_fp8_f32(p0[4 * g + 2], p0[4 * g + 3], w, true);
;     int u = __builtin_amdgcn_cvt_pk_fp8_f32(p1[4 * g], p1[4 * g + 1], 0, false); p8[4 + g] = __builtin_amdgcn_cvt_pk_fp8_f32(p1[4 * g + 2], p1[4 * g + 3], u, true); }
; }
; __device__ __forceinline__ void pv8(f32x16* o, const char* Vt, const v8i32 p8, int r32, int hi) {
;   const int sw = (r32 >> 2) & 3, a0 = r32 * 64 + (((hi * 2) ^ sw) << 4), a1 = r32 * 64 + (((hi * 2 + 1) ^ sw) << 4);
; #pragma unroll
;   for (int d0 = 0; d0 < 4; ++d0) {
;     const v8i32 vf = cat8(*reinterpret_cast<const v4i32*>(Vt + d0 * 2048 + a0), *reinterpret_cast<const v4i32*>(Vt + d0 * 2048 + a1));
;     o[d0] = __builtin_amdgcn_mfma_scale_f32_32x32x64_f8f6f4(p8, vf, o[d0], 0, 0, 0, 127, 0, 127); }
; }
; __device__ __forceinline__ void qkt9(f32x16& p0, f32x16& p1, const char* Kn, const char* Kr, const v8i32* qf, const float init, int r32, int hi) {
; #pragma unroll
;   for (int r = 0; r < 16; ++r) { p0[r] = init; p1[r] = init; }
; #pragma unroll
;   for (int s = 0; s < 2; ++s) { const int c0 = s * 4 + hi * 2;
;     const v8i32 a0 = cat8(*reinterpret_cast<const v4i32*>(Kn + KN8SW(r32, c0)), *reinterpret_cast<const v4i32*>(Kn + KN8SW(r32, c0 + 1)));
;     const v8i32 a1 = cat8(*reinterpret_cast<const v4i32*>(Kn + 4096 + KN8SW(r32, c0)), *reinterpret_cast<const v4i32*>(Kn + 4096 + KN8SW(r32, c0 + 1)));
;     p0 = __builtin_amdgcn_mfma_scale_f32_32x32x64_f8f6f4(a0, qf[s], p0, 0, 0, 0, 127, 0, 124);
;     p1 = __builtin_amdgcn_mfma_scale_f32_32x32x64_f8f6f4(a1, qf[s], p1, 0, 0, 0, 127, 0, 124); }
;   { const int c0 = hi * 2;
.Lmla_q0_cont:
	ds_read_b128 v[82:85], v215 offset:51200
	ds_read_b128 v[86:89], v216 offset:51200
	ds_read_b128 v[222:225], v215 offset:55296
	ds_read_b128 v[226:229], v216 offset:55296
	v_exp_f32_e32 v0, v114
	v_exp_f32_e32 v177, v115
	v_exp_f32_e32 v179, v116
	v_exp_f32_e32 v254, v117
	v_add_f32_e32 v219, v0, v177
	v_cvt_pk_fp8_f32 v246, v0, v177
	v_add_f32_e32 v219, v179, v219
	v_add_f32_e32 v219, v254, v219
	v_cvt_pk_fp8_f32 v246, v179, v254 op_sel:[0,0,1]
	s_waitcnt lgkmcnt(2)
	v_mfma_scale_f32_32x32x64_f8f6f4 v[82:97], v[82:89], v[146:153], v[230:245], v194, v193 op_sel_hi:[0,0,0]
	v_exp_f32_e32 v0, v118
	v_exp_f32_e32 v177, v119
	v_exp_f32_e32 v179, v120
	v_exp_f32_e32 v254, v121
	v_add_f32_e32 v219, v0, v219
	v_add_f32_e32 v219, v177, v219
	v_cvt_pk_fp8_f32 v247, v0, v177
	v_add_f32_e32 v219, v179, v219
	v_add_f32_e32 v219, v254, v219
	v_cvt_pk_fp8_f32 v247, v179, v254 op_sel:[0,0,1]
	ds_read_b128 v[114:117], v213 offset:51200
	ds_read_b128 v[118:121], v214 offset:51200
	s_waitcnt lgkmcnt(2)
	v_mfma_scale_f32_32x32x64_f8f6f4 v[66:81], v[222:229], v[146:153], v[230:245], v194, v193 op_sel_hi:[0,0,0]
	ds_read_b128 v[222:225], v213 offset:55296
	ds_read_b128 v[226:229], v214 offset:55296
	v_exp_f32_e32 v0, v122
	v_exp_f32_e32 v177, v123
	v_exp_f32_e32 v179, v124
	v_exp_f32_e32 v254, v125
	v_add_f32_e32 v219, v0, v219
	v_add_f32_e32 v219, v177, v219
	v_cvt_pk_fp8_f32 v248, v0, v177
	v_add_f32_e32 v219, v179, v219
	v_add_f32_e32 v219, v254, v219
	v_cvt_pk_fp8_f32 v248, v179, v254 op_sel:[0,0,1]
	v_exp_f32_e32 v0, v126
	v_exp_f32_e32 v177, v127
	v_exp_f32_e32 v179, v128
	v_exp_f32_e32 v254, v129
	v_add_f32_e32 v219, v0, v219
	v_add_f32_e32 v219, v177, v219
	v_cvt_pk_fp8_f32 v249, v0, v177
	v_add_f32_e32 v219, v179, v219
	v_add_f32_e32 v219, v254, v219
	v_cvt_pk_fp8_f32 v249, v179, v254 op_sel:[0,0,1]
	ds_read_b128 v[122:125], v185 offset:59392
	ds_read_b128 v[126:129], v186 offset:59392
	s_waitcnt lgkmcnt(4)
	v_mfma_scale_f32_32x32x64_f8f6f4 v[82:97], v[114:121], v[138:145], v[82:97], v194, v193 op_sel_hi:[0,0,0]
	v_exp_f32_e32 v0, v98
	v_exp_f32_e32 v177, v99
	v_exp_f32_e32 v179, v100
	v_exp_f32_e32 v254, v101
	v_add_f32_e32 v219, v0, v219
	v_add_f32_e32 v219, v177, v219
	v_cvt_pk_fp8_f32 v250, v0, v177
	v_add_f32_e32 v219, v179, v219
	v_add_f32_e32 v219, v254, v219
	v_cvt_pk_fp8_f32 v250, v179, v254 op_sel:[0,0,1]
	s_waitcnt lgkmcnt(2)
	v_mfma_scale_f32_32x32x64_f8f6f4 v[66:81], v[222:229], v[138:145], v[66:81], v194, v193 op_sel_hi:[0,0,0]
	ds_read_b128 v[222:225], v185 offset:61440
	ds_read_b128 v[226:229], v186 offset:61440
	v_exp_f32_e32 v0, v102
	v_exp_f32_e32 v177, v103
	v_exp_f32_e32 v179, v104
	v_exp_f32_e32 v254, v105
	v_add_f32_e32 v219, v0, v219
	v_add_f32_e32 v219, v177, v219
	v_cvt_pk_fp8_f32 v251, v0, v177
	v_add_f32_e32 v219, v179, v219
	v_add_f32_e32 v219, v254, v219
	v_cvt_pk_fp8_f32 v251, v179, v254 op_sel:[0,0,1]
	v_exp_f32_e32 v0, v106
	v_exp_f32_e32 v177, v107
	v_exp_f32_e32 v179, v108
	v_exp_f32_e32 v254, v109
	v_add_f32_e32 v219, v0, v219
	v_add_f32_e32 v219, v177, v219
	v_cvt_pk_fp8_f32 v252, v0, v177
	v_add_f32_e32 v219, v179, v219
	v_add_f32_e32 v219, v254, v219
	v_cvt_pk_fp8_f32 v252, v179, v254 op_sel:[0,0,1]
	s_waitcnt lgkmcnt(2)
	v_mfma_scale_f32_32x32x64_f8f6f4 v[82:97], v[122:129], v[130:137], v[82:97], v194, v193 op_sel_hi:[0,0,0]
	v_exp_f32_e32 v0, v110
	v_exp_f32_e32 v177, v111
	v_exp_f32_e32 v179, v112
	v_exp_f32_e32 v254, v113
	v_add_f32_e32 v219, v0, v219
	v_add_f32_e32 v219, v177, v219
	v_cvt_pk_fp8_f32 v253, v0, v177
	v_add_f32_e32 v219, v179, v219
	v_add_f32_e32 v219, v254, v219
	v_cvt_pk_fp8_f32 v253, v179, v254 op_sel:[0,0,1]
	ds_read_b128 v[122:125], v185 offset:8192
	ds_read_b128 v[126:129], v186 offset:8192
	ds_read_b128 v[114:117], v185 offset:10240
	ds_read_b128 v[118:121], v186 offset:10240
	ds_read_b128 v[106:109], v185 offset:12288
	ds_read_b128 v[110:113], v186 offset:12288
	ds_read_b128 v[98:101], v185 offset:14336
	ds_read_b128 v[102:105], v186 offset:14336
	s_waitcnt lgkmcnt(8)
	v_mfma_scale_f32_32x32x64_f8f6f4 v[66:81], v[222:229], v[130:137], v[66:81], v194, v193 op_sel_hi:[0,0,0]
	v_mov_b32_e32 v0, v219
	s_nop 1
	v_permlane32_swap_b32_e32 v219, v0
	v_add_f32_e32 v219, v219, v0
	v_fma_f32 v209, v209, v221, v219
	v_max_f32_e32 v177, v82, v83
	v_max3_f32 v177, v177, v84, v85
	v_max3_f32 v177, v177, v86, v87
	v_max3_f32 v177, v177, v88, v89
	v_max3_f32 v177, v177, v90, v91
	v_max3_f32 v177, v177, v92, v93
	v_max3_f32 v177, v177, v94, v95
	v_max3_f32 v177, v177, v96, v97
	s_waitcnt lgkmcnt(6)
	v_mfma_scale_f32_32x32x64_f8f6f4 v[50:65], v[246:253], v[122:129], v[50:65], v194, v194 op_sel_hi:[0,0,0]
	s_waitcnt lgkmcnt(4)
	v_mfma_scale_f32_32x32x64_f8f6f4 v[34:49], v[246:253], v[114:121], v[34:49], v194, v194 op_sel_hi:[0,0,0]
	s_waitcnt vmcnt(0)
	s_waitcnt lgkmcnt(0)
	s_barrier
	v_max_f32_e32 v0, v66, v67
	v_max3_f32 v0, v0, v68, v69
	v_max3_f32 v0, v0, v70, v71
	v_max3_f32 v0, v0, v72, v73
	s_waitcnt lgkmcnt(2)
	v_mfma_scale_f32_32x32x64_f8f6f4 v[18:33], v[246:253], v[106:113], v[18:33], v194, v194 op_sel_hi:[0,0,0]
	v_max3_f32 v0, v0, v74, v75
	v_max3_f32 v0, v0, v76, v77
	v_max3_f32 v0, v0, v78, v79
	v_max3_f32 v0, v0, v80, v81
	s_waitcnt lgkmcnt(0)
	v_mfma_scale_f32_32x32x64_f8f6f4 v[2:17], v[246:253], v[98:105], v[2:17], v194, v194 op_sel_hi:[0,0,0]
	v_max_f32_e32 v177, v177, v0
	v_mov_b32_e32 v0, v177
	v_mov_b32_e32 v218, 1.0
	s_nop 0
	v_permlane32_swap_b32_e32 v177, v0
	v_max_f32_e32 v177, v177, v0
	v_cmp_nge_f32_e32 vcc, s90, v177
	s_cbranch_vccnz .Lmla_q1_newmax
